# re-measure k15 paired (quick timings drifted)
# baseline (speedup 1.0000x reference)
.Lgsk0_loop:
	s_add_i32 s9, s8, 0xfffe8000
	s_and_b32 s10, s8, 0x18000
	s_and_b32 s9, s9, 0x18000
	s_add_i32 s10, s7, s10
	v_add_u32_e32 v112, s9, v135
	v_or_b32_e32 v139, s9, v137
	s_add_i32 s18, s10, 0x400
	s_add_i32 s11, s10, 0x800
	s_add_i32 s9, s10, 0xc00
	s_add_i32 s8, s8, 0x8000
	s_cmp_eq_u32 s8, 0x100000
	s_waitcnt vmcnt(8) lgkmcnt(0)
	s_barrier
	v_mfma_f32_16x16x32_bf16 v[60:63], v[158:161], v[232:235], v[60:63]
	ds_read_b128 v[186:189], v112
	ds_read_b128 v[190:193], v112 offset:1024
	v_mfma_f32_16x16x32_bf16 v[44:47], v[158:161], v[236:239], v[44:47]
	ds_read_b128 v[194:197], v112 offset:2048
	ds_read_b128 v[198:201], v112 offset:3072
	v_mfma_f32_16x16x32_bf16 v[28:31], v[158:161], v[240:243], v[28:31]
	s_mov_b32 m0, s10
	v_mfma_f32_16x16x32_bf16 v[12:15], v[158:161], v[244:247], v[12:15]
	global_load_lds_dwordx4 v[154:155], off
	v_lshl_add_u64 v[154:155], v[154:155], 0, 64
	v_mfma_f32_16x16x32_bf16 v[56:59], v[162:165], v[232:235], v[56:59]
	ds_read_b128 v[158:161], v139
	v_mfma_f32_16x16x32_bf16 v[40:43], v[162:165], v[236:239], v[40:43]
	v_mfma_f32_16x16x32_bf16 v[24:27], v[162:165], v[240:243], v[24:27]
	s_mov_b32 m0, s18
	v_mfma_f32_16x16x32_bf16 v[8:11], v[162:165], v[244:247], v[8:11]
	global_load_lds_dwordx4 v[152:153], off
	v_lshl_add_u64 v[152:153], v[152:153], 0, 64
	v_mfma_f32_16x16x32_bf16 v[52:55], v[166:169], v[232:235], v[52:55]
	ds_read_b128 v[162:165], v139 offset:1024
	v_mfma_f32_16x16x32_bf16 v[36:39], v[166:169], v[236:239], v[36:39]
	v_mfma_f32_16x16x32_bf16 v[20:23], v[166:169], v[240:243], v[20:23]
	s_mov_b32 m0, s11
	v_mfma_f32_16x16x32_bf16 v[4:7], v[166:169], v[244:247], v[4:7]
	global_load_lds_dwordx4 v[150:151], off
	v_lshl_add_u64 v[150:151], v[150:151], 0, 64
	v_mfma_f32_16x16x32_bf16 v[48:51], v[182:185], v[232:235], v[48:51]
	ds_read_b128 v[166:169], v139 offset:2048
	v_mfma_f32_16x16x32_bf16 v[32:35], v[182:185], v[236:239], v[32:35]
	v_mfma_f32_16x16x32_bf16 v[16:19], v[182:185], v[240:243], v[16:19]
	s_mov_b32 m0, s9
	v_mfma_f32_16x16x32_bf16 v[0:3], v[182:185], v[244:247], v[0:3]
	global_load_lds_dwordx4 v[148:149], off
	v_lshl_add_u64 v[148:149], v[148:149], 0, 64
	s_waitcnt lgkmcnt(2)
	v_mfma_f32_16x16x32_bf16 v[126:129], v[158:161], v[186:189], v[126:129]
	ds_read_b128 v[182:185], v139 offset:3072
	v_mfma_f32_16x16x32_bf16 v[108:111], v[158:161], v[190:193], v[108:111]
	ds_read_b128 v[232:235], v112 offset:4096
	ds_read_b128 v[236:239], v112 offset:5120
	v_mfma_f32_16x16x32_bf16 v[92:95], v[158:161], v[194:197], v[92:95]
	ds_read_b128 v[240:243], v112 offset:6144
	ds_read_b128 v[244:247], v112 offset:7168
	v_mfma_f32_16x16x32_bf16 v[76:79], v[158:161], v[198:201], v[76:79]
	s_waitcnt lgkmcnt(6)
	v_mfma_f32_16x16x32_bf16 v[122:125], v[162:165], v[186:189], v[122:125]
	v_mfma_f32_16x16x32_bf16 v[104:107], v[162:165], v[190:193], v[104:107]
	v_mfma_f32_16x16x32_bf16 v[88:91], v[162:165], v[194:197], v[88:91]
	v_mfma_f32_16x16x32_bf16 v[72:75], v[162:165], v[198:201], v[72:75]
	s_waitcnt lgkmcnt(5)
	v_mfma_f32_16x16x32_bf16 v[118:121], v[166:169], v[186:189], v[118:121]
	v_mfma_f32_16x16x32_bf16 v[100:103], v[166:169], v[190:193], v[100:103]
	v_mfma_f32_16x16x32_bf16 v[84:87], v[166:169], v[194:197], v[84:87]
	v_mfma_f32_16x16x32_bf16 v[68:71], v[166:169], v[198:201], v[68:71]
	s_waitcnt lgkmcnt(4)
	v_mfma_f32_16x16x32_bf16 v[114:117], v[182:185], v[186:189], v[114:117]
	v_mfma_f32_16x16x32_bf16 v[96:99], v[182:185], v[190:193], v[96:99]
	v_mfma_f32_16x16x32_bf16 v[80:83], v[182:185], v[194:197], v[80:83]
	v_mfma_f32_16x16x32_bf16 v[64:67], v[182:185], v[198:201], v[64:67]
	s_cbranch_scc0 .Lgsk0_loop
	s_waitcnt lgkmcnt(0)
	v_mfma_f32_16x16x32_bf16 v[60:63], v[158:161], v[232:235], v[60:63]
	v_mfma_f32_16x16x32_bf16 v[44:47], v[158:161], v[236:239], v[44:47]
	v_mfma_f32_16x16x32_bf16 v[28:31], v[158:161], v[240:243], v[28:31]
	v_mfma_f32_16x16x32_bf16 v[12:15], v[158:161], v[244:247], v[12:15]
	v_mfma_f32_16x16x32_bf16 v[56:59], v[162:165], v[232:235], v[56:59]
	v_mfma_f32_16x16x32_bf16 v[40:43], v[162:165], v[236:239], v[40:43]
	v_mfma_f32_16x16x32_bf16 v[24:27], v[162:165], v[240:243], v[24:27]
	v_mfma_f32_16x16x32_bf16 v[8:11], v[162:165], v[244:247], v[8:11]
	v_mfma_f32_16x16x32_bf16 v[52:55], v[166:169], v[232:235], v[52:55]
	v_mfma_f32_16x16x32_bf16 v[36:39], v[166:169], v[236:239], v[36:39]
	v_mfma_f32_16x16x32_bf16 v[20:23], v[166:169], v[240:243], v[20:23]
	v_mfma_f32_16x16x32_bf16 v[4:7], v[166:169], v[244:247], v[4:7]
	v_mfma_f32_16x16x32_bf16 v[48:51], v[182:185], v[232:235], v[48:51]
	v_mfma_f32_16x16x32_bf16 v[32:35], v[182:185], v[236:239], v[32:35]
	v_mfma_f32_16x16x32_bf16 v[16:19], v[182:185], v[240:243], v[16:19]
	v_mfma_f32_16x16x32_bf16 v[0:3], v[182:185], v[244:247], v[0:3]
	s_waitcnt vmcnt(8)
	s_barrier
	v_add_u32_e32 v112, 0x8000, v135
	v_or_b32_e32 v139, 0x8000, v137
	ds_read_b128 v[148:151], v139
	ds_read_b128 v[152:155], v139 offset:1024
	ds_read_b128 v[158:161], v139 offset:2048
	ds_read_b128 v[162:165], v139 offset:3072
	ds_read_b128 v[166:169], v112
	ds_read_b128 v[182:185], v112 offset:1024
	ds_read_b128 v[186:189], v112 offset:2048
	ds_read_b128 v[190:193], v112 offset:3072
	v_or_b32_e32 v139, 0x10000, v137
	s_waitcnt lgkmcnt(0)
	s_lshl_b32 s7, s4, 8
	v_mfma_f32_16x16x32_bf16 v[126:129], v[148:151], v[166:169], v[126:129]
	s_and_b32 s4, s4, 0xc0
	s_and_b32 s78, s7, 0xffffc000
	s_or_b32 s8, s5, s4
	v_mfma_f32_16x16x32_bf16 v[122:125], v[152:155], v[166:169], v[122:125]
	s_mov_b64 s[4:5], -1
	s_cmpk_gt_i32 s8, 0x17f
	v_mfma_f32_16x16x32_bf16 v[118:121], v[158:161], v[166:169], v[118:121]
	v_mfma_f32_16x16x32_bf16 v[114:117], v[162:165], v[166:169], v[114:117]
	v_mfma_f32_16x16x32_bf16 v[108:111], v[148:151], v[182:185], v[108:111]
	v_mfma_f32_16x16x32_bf16 v[104:107], v[152:155], v[182:185], v[104:107]
	v_mfma_f32_16x16x32_bf16 v[100:103], v[158:161], v[182:185], v[100:103]
	v_mfma_f32_16x16x32_bf16 v[96:99], v[162:165], v[182:185], v[96:99]
	v_mfma_f32_16x16x32_bf16 v[92:95], v[148:151], v[186:189], v[92:95]
	v_mfma_f32_16x16x32_bf16 v[88:91], v[152:155], v[186:189], v[88:91]
	v_mfma_f32_16x16x32_bf16 v[84:87], v[158:161], v[186:189], v[84:87]
	v_mfma_f32_16x16x32_bf16 v[80:83], v[162:165], v[186:189], v[80:83]
	v_mfma_f32_16x16x32_bf16 v[76:79], v[148:151], v[190:193], v[76:79]
	v_mfma_f32_16x16x32_bf16 v[72:75], v[152:155], v[190:193], v[72:75]
	v_mfma_f32_16x16x32_bf16 v[68:71], v[158:161], v[190:193], v[68:71]
	v_mfma_f32_16x16x32_bf16 v[64:67], v[162:165], v[190:193], v[64:67]
	ds_read_b128 v[166:169], v112 offset:4096
	ds_read_b128 v[182:185], v112 offset:5120
	ds_read_b128 v[186:189], v112 offset:6144
	ds_read_b128 v[190:193], v112 offset:7168
	s_waitcnt lgkmcnt(0)
	s_waitcnt vmcnt(4)
	s_barrier
	v_mfma_f32_16x16x32_bf16 v[60:63], v[148:151], v[166:169], v[60:63]
	v_add_u32_e32 v112, 0x10000, v135
	v_mfma_f32_16x16x32_bf16 v[56:59], v[152:155], v[166:169], v[56:59]
	v_mfma_f32_16x16x32_bf16 v[52:55], v[158:161], v[166:169], v[52:55]
	v_mfma_f32_16x16x32_bf16 v[48:51], v[162:165], v[166:169], v[48:51]
	v_mfma_f32_16x16x32_bf16 v[44:47], v[148:151], v[182:185], v[44:47]
	v_mfma_f32_16x16x32_bf16 v[40:43], v[152:155], v[182:185], v[40:43]
	v_mfma_f32_16x16x32_bf16 v[36:39], v[158:161], v[182:185], v[36:39]
	v_mfma_f32_16x16x32_bf16 v[32:35], v[162:165], v[182:185], v[32:35]
	v_mfma_f32_16x16x32_bf16 v[28:31], v[148:151], v[186:189], v[28:31]
	v_mfma_f32_16x16x32_bf16 v[24:27], v[152:155], v[186:189], v[24:27]
	v_mfma_f32_16x16x32_bf16 v[20:23], v[158:161], v[186:189], v[20:23]
	v_mfma_f32_16x16x32_bf16 v[16:19], v[162:165], v[186:189], v[16:19]
	v_mfma_f32_16x16x32_bf16 v[12:15], v[148:151], v[190:193], v[12:15]
	v_mfma_f32_16x16x32_bf16 v[8:11], v[152:155], v[190:193], v[8:11]
	v_mfma_f32_16x16x32_bf16 v[4:7], v[158:161], v[190:193], v[4:7]
	v_mfma_f32_16x16x32_bf16 v[0:3], v[162:165], v[190:193], v[0:3]
	ds_read_b128 v[148:151], v139
	ds_read_b128 v[152:155], v139 offset:1024
	ds_read_b128 v[158:161], v139 offset:2048
	ds_read_b128 v[162:165], v139 offset:3072
	ds_read_b128 v[166:169], v112
	ds_read_b128 v[182:185], v112 offset:1024
	ds_read_b128 v[186:189], v112 offset:2048
	ds_read_b128 v[190:193], v112 offset:3072
	s_nop 0
	s_waitcnt lgkmcnt(0)
	s_nop 0
	v_mfma_f32_16x16x32_bf16 v[126:129], v[148:151], v[166:169], v[126:129]
	v_mfma_f32_16x16x32_bf16 v[122:125], v[152:155], v[166:169], v[122:125]
	v_mfma_f32_16x16x32_bf16 v[118:121], v[158:161], v[166:169], v[118:121]
	v_mfma_f32_16x16x32_bf16 v[114:117], v[162:165], v[166:169], v[114:117]
	v_mfma_f32_16x16x32_bf16 v[108:111], v[148:151], v[182:185], v[108:111]
	v_mfma_f32_16x16x32_bf16 v[104:107], v[152:155], v[182:185], v[104:107]
	v_mfma_f32_16x16x32_bf16 v[100:103], v[158:161], v[182:185], v[100:103]
	v_mfma_f32_16x16x32_bf16 v[96:99], v[162:165], v[182:185], v[96:99]
	v_mfma_f32_16x16x32_bf16 v[92:95], v[148:151], v[186:189], v[92:95]
	v_mfma_f32_16x16x32_bf16 v[88:91], v[152:155], v[186:189], v[88:91]
	v_mfma_f32_16x16x32_bf16 v[84:87], v[158:161], v[186:189], v[84:87]
	v_mfma_f32_16x16x32_bf16 v[80:83], v[162:165], v[186:189], v[80:83]
	v_mfma_f32_16x16x32_bf16 v[76:79], v[148:151], v[190:193], v[76:79]
	v_mfma_f32_16x16x32_bf16 v[72:75], v[152:155], v[190:193], v[72:75]
	v_mfma_f32_16x16x32_bf16 v[68:71], v[158:161], v[190:193], v[68:71]
	v_mfma_f32_16x16x32_bf16 v[64:67], v[162:165], v[190:193], v[64:67]
	ds_read_b128 v[166:169], v112 offset:4096
	ds_read_b128 v[182:185], v112 offset:5120
	ds_read_b128 v[186:189], v112 offset:6144
	ds_read_b128 v[190:193], v112 offset:7168
	s_waitcnt lgkmcnt(0)
	s_waitcnt vmcnt(0)
	s_barrier
	v_mfma_f32_16x16x32_bf16 v[60:63], v[148:151], v[166:169], v[60:63]
	v_add_u32_e32 v112, 0x18000, v135
	v_or_b32_e32 v135, 0x18000, v137
	v_mfma_f32_16x16x32_bf16 v[56:59], v[152:155], v[166:169], v[56:59]
	v_bfe_u32 v137, v131, 4, 2
	v_mfma_f32_16x16x32_bf16 v[52:55], v[158:161], v[166:169], v[52:55]
	v_mfma_f32_16x16x32_bf16 v[48:51], v[162:165], v[166:169], v[48:51]
	v_mfma_f32_16x16x32_bf16 v[44:47], v[148:151], v[182:185], v[44:47]
	v_mfma_f32_16x16x32_bf16 v[40:43], v[152:155], v[182:185], v[40:43]
	v_mfma_f32_16x16x32_bf16 v[36:39], v[158:161], v[182:185], v[36:39]
	v_mfma_f32_16x16x32_bf16 v[32:35], v[162:165], v[182:185], v[32:35]
	v_mfma_f32_16x16x32_bf16 v[28:31], v[148:151], v[186:189], v[28:31]
	v_mfma_f32_16x16x32_bf16 v[24:27], v[152:155], v[186:189], v[24:27]
	v_mfma_f32_16x16x32_bf16 v[20:23], v[158:161], v[186:189], v[20:23]
	v_mfma_f32_16x16x32_bf16 v[16:19], v[162:165], v[186:189], v[16:19]
	v_mfma_f32_16x16x32_bf16 v[12:15], v[148:151], v[190:193], v[12:15]
	v_mfma_f32_16x16x32_bf16 v[8:11], v[152:155], v[190:193], v[8:11]
	v_mfma_f32_16x16x32_bf16 v[4:7], v[158:161], v[190:193], v[4:7]
	v_mfma_f32_16x16x32_bf16 v[0:3], v[162:165], v[190:193], v[0:3]
	ds_read_b128 v[164:167], v135
	ds_read_b128 v[168:171], v135 offset:1024
	ds_read_b128 v[182:185], v135 offset:2048
	ds_read_b128 v[186:189], v135 offset:3072
	ds_read_b128 v[148:151], v112
	ds_read_b128 v[152:155], v112 offset:1024
	ds_read_b128 v[158:161], v112 offset:2048
	ds_read_b128 v[190:193], v112 offset:3072
	v_or_b32_e32 v162, 16, v144
	s_waitcnt lgkmcnt(0)
	v_ashrrev_i32_e32 v163, 31, v162
	v_mfma_f32_16x16x32_bf16 v[126:129], v[164:167], v[148:151], v[126:129]
	v_and_b32_e32 v135, 63, v131
	v_mfma_f32_16x16x32_bf16 v[122:125], v[168:171], v[148:151], v[122:125]
	v_mfma_f32_16x16x32_bf16 v[118:121], v[182:185], v[148:151], v[118:121]
	v_mfma_f32_16x16x32_bf16 v[114:117], v[186:189], v[148:151], v[114:117]
	v_mfma_f32_16x16x32_bf16 v[108:111], v[164:167], v[152:155], v[108:111]
	v_mfma_f32_16x16x32_bf16 v[104:107], v[168:171], v[152:155], v[104:107]
	v_mfma_f32_16x16x32_bf16 v[100:103], v[182:185], v[152:155], v[100:103]
	v_mfma_f32_16x16x32_bf16 v[96:99], v[186:189], v[152:155], v[96:99]
	v_mfma_f32_16x16x32_bf16 v[92:95], v[164:167], v[158:161], v[92:95]
	v_mfma_f32_16x16x32_bf16 v[88:91], v[168:171], v[158:161], v[88:91]
	v_mfma_f32_16x16x32_bf16 v[84:87], v[182:185], v[158:161], v[84:87]
	v_mfma_f32_16x16x32_bf16 v[80:83], v[186:189], v[158:161], v[80:83]
	v_or_b32_e32 v160, 32, v144
	v_or_b32_e32 v158, 48, v144
	v_ashrrev_i32_e32 v161, 31, v160
	v_mfma_f32_16x16x32_bf16 v[76:79], v[164:167], v[190:193], v[76:79]
	v_ashrrev_i32_e32 v159, 31, v158
	v_mfma_f32_16x16x32_bf16 v[72:75], v[168:171], v[190:193], v[72:75]
	v_mfma_f32_16x16x32_bf16 v[68:71], v[182:185], v[190:193], v[68:71]
	v_mfma_f32_16x16x32_bf16 v[64:67], v[186:189], v[190:193], v[64:67]
	ds_read_b128 v[148:151], v112 offset:4096
	ds_read_b128 v[152:155], v112 offset:5120
	ds_read_b128 v[190:193], v112 offset:6144
	ds_read_b128 v[194:197], v112 offset:7168
	s_waitcnt lgkmcnt(0)
	s_barrier
	v_mfma_f32_16x16x32_bf16 v[60:63], v[164:167], v[148:151], v[60:63]
	v_mfma_f32_16x16x32_bf16 v[56:59], v[168:171], v[148:151], v[56:59]
	v_mfma_f32_16x16x32_bf16 v[52:55], v[182:185], v[148:151], v[52:55]
	v_mfma_f32_16x16x32_bf16 v[48:51], v[186:189], v[148:151], v[48:51]
	v_or_b32_e32 v150, 0x60, v144
	v_or_b32_e32 v148, 0x70, v144
	v_ashrrev_i32_e32 v151, 31, v150
	v_mfma_f32_16x16x32_bf16 v[44:47], v[164:167], v[152:155], v[44:47]
	v_ashrrev_i32_e32 v149, 31, v148
	v_mfma_f32_16x16x32_bf16 v[40:43], v[168:171], v[152:155], v[40:43]
	v_mfma_f32_16x16x32_bf16 v[36:39], v[182:185], v[152:155], v[36:39]
	v_mfma_f32_16x16x32_bf16 v[32:35], v[186:189], v[152:155], v[32:35]
	v_or_b32_e32 v154, 64, v144
	v_or_b32_e32 v152, 0x50, v144
	v_ashrrev_i32_e32 v155, 31, v154
	v_mfma_f32_16x16x32_bf16 v[28:31], v[164:167], v[190:193], v[28:31]
	v_ashrrev_i32_e32 v153, 31, v152
	v_mfma_f32_16x16x32_bf16 v[24:27], v[168:171], v[190:193], v[24:27]
	v_mfma_f32_16x16x32_bf16 v[20:23], v[182:185], v[190:193], v[20:23]
	v_mfma_f32_16x16x32_bf16 v[16:19], v[186:189], v[190:193], v[16:19]
	v_mfma_f32_16x16x32_bf16 v[12:15], v[164:167], v[194:197], v[12:15]
	v_mfma_f32_16x16x32_bf16 v[8:11], v[168:171], v[194:197], v[8:11]
	v_mfma_f32_16x16x32_bf16 v[4:7], v[182:185], v[194:197], v[4:7]
	v_mfma_f32_16x16x32_bf16 v[0:3], v[186:189], v[194:197], v[0:3]
	s_cbranch_scc0 .LBB0_213
	s_cmpk_gt_u32 s8, 0x57f
	s_cbranch_scc0 .LBB0_210
	s_cmpk_lg_i32 s8, 0x580
	s_cbranch_scc1 .LBB0_209
	v_lshlrev_b32_e32 v112, 7, v144
	v_and_b32_e32 v112, 0x7c780, v112
	v_lshl_add_u64 v[164:165], s[46:47], 0, v[112:113]
	v_lshlrev_b32_e32 v112, 5, v137
	v_lshl_add_u64 v[168:169], v[164:165], 0, v[112:113]
	global_load_dwordx4 v[164:167], v[168:169], off offset:16
	s_nop 0
	global_load_dwordx4 v[168:171], v[168:169], off
	v_pk_mul_f32 v[184:185], v[146:147], v[122:123] op_sel_hi:[0,1]
	v_pk_mul_f32 v[176:177], v[146:147], v[126:127] op_sel_hi:[0,1]
	v_pk_mul_f32 v[182:183], v[146:147], v[124:125] op_sel_hi:[0,1]
	v_pk_mul_f32 v[174:175], v[146:147], v[128:129] op_sel_hi:[0,1]
	v_lshlrev_b32_e32 v139, 7, v162
	s_waitcnt vmcnt(0)
	v_mov_b32_e32 v186, v168
	v_mov_b32_e32 v187, v170
	v_mov_b32_e32 v170, v169
	v_pk_mul_f32 v[168:169], v[184:185], v[170:171]
	v_pk_mul_f32 v[184:185], v[184:185], v[186:187]
	v_pk_fma_f32 v[168:169], v[176:177], v[186:187], v[168:169] neg_lo:[0,0,1] neg_hi:[0,0,1]
	v_pk_fma_f32 v[170:171], v[176:177], v[170:171], v[184:185]
	v_mov_b32_e32 v177, v166
	v_mov_b32_e32 v166, v165
	v_mov_b32_e32 v176, v164
	v_pk_mul_f32 v[164:165], v[182:183], v[166:167]
	v_cvt_pk_bf16_f32 v168, v168, v169
	v_pk_fma_f32 v[164:165], v[174:175], v[176:177], v[164:165] neg_lo:[0,0,1] neg_hi:[0,0,1]
	v_pk_mul_f32 v[176:177], v[182:183], v[176:177]
	v_cvt_pk_bf16_f32 v169, v164, v165
	v_lshlrev_b64 v[164:165], 6, v[144:145]
	v_pk_fma_f32 v[166:167], v[174:175], v[166:167], v[176:177]
	v_lshl_add_u64 v[174:175], s[36:37], 0, v[164:165]
	v_lshlrev_b32_e32 v164, 3, v137
	v_mov_b32_e32 v165, v113
	v_lshl_add_u64 v[174:175], v[174:175], 0, v[164:165]
	global_store_dwordx2 v[174:175], v[168:169], off
	v_cvt_pk_bf16_f32 v169, v166, v167
	v_and_b32_e32 v166, 0x7cf80, v139
	v_mov_b32_e32 v167, v113
	v_cvt_pk_bf16_f32 v168, v170, v171
	v_lshl_add_u64 v[166:167], s[46:47], 0, v[166:167]
	global_store_dwordx2 v[174:175], v[168:169], off offset:32
	v_lshl_add_u64 v[182:183], v[166:167], 0, v[112:113]
	global_load_dwordx4 v[166:169], v[182:183], off offset:16
	s_nop 0
	global_load_dwordx4 v[182:185], v[182:183], off
	v_pk_mul_f32 v[186:187], v[142:143], v[104:105] op_sel_hi:[0,1]
	v_pk_mul_f32 v[174:175], v[142:143], v[108:109] op_sel_hi:[0,1]
	v_pk_mul_f32 v[176:177], v[142:143], v[106:107] op_sel_hi:[0,1]
	v_pk_mul_f32 v[170:171], v[142:143], v[110:111] op_sel_hi:[0,1]
	v_lshlrev_b32_e32 v139, 7, v160
	s_waitcnt vmcnt(0)
	v_mov_b32_e32 v188, v182
	v_mov_b32_e32 v189, v184
	v_mov_b32_e32 v184, v183
	v_pk_mul_f32 v[182:183], v[186:187], v[184:185]
	v_pk_mul_f32 v[186:187], v[186:187], v[188:189]
	v_pk_fma_f32 v[182:183], v[174:175], v[188:189], v[182:183] neg_lo:[0,0,1] neg_hi:[0,0,1]
	v_pk_fma_f32 v[174:175], v[174:175], v[184:185], v[186:187]
	v_mov_b32_e32 v185, v168
	v_mov_b32_e32 v168, v167
	v_mov_b32_e32 v184, v166
	v_pk_mul_f32 v[166:167], v[176:177], v[168:169]
	v_pk_mul_f32 v[176:177], v[176:177], v[184:185]
	v_pk_fma_f32 v[166:167], v[170:171], v[184:185], v[166:167] neg_lo:[0,0,1] neg_hi:[0,0,1]
	v_pk_fma_f32 v[168:169], v[170:171], v[168:169], v[176:177]
	v_cvt_pk_bf16_f32 v171, v166, v167
	v_lshlrev_b64 v[166:167], 6, v[162:163]
	v_lshl_add_u64 v[166:167], s[36:37], 0, v[166:167]
	v_cvt_pk_bf16_f32 v170, v182, v183
	v_lshl_add_u64 v[166:167], v[166:167], 0, v[164:165]
	global_store_dwordx2 v[166:167], v[170:171], off
	v_cvt_pk_bf16_f32 v170, v174, v175
	v_cvt_pk_bf16_f32 v171, v168, v169
	global_store_dwordx2 v[166:167], v[170:171], off offset:32
	v_and_b32_e32 v166, 0x7d780, v139
	v_mov_b32_e32 v167, v113
	v_lshl_add_u64 v[166:167], s[46:47], 0, v[166:167]
	v_lshl_add_u64 v[182:183], v[166:167], 0, v[112:113]
	global_load_dwordx4 v[166:169], v[182:183], off offset:16
	s_nop 0
	global_load_dwordx4 v[182:185], v[182:183], off
	v_pk_mul_f32 v[186:187], v[140:141], v[88:89] op_sel_hi:[0,1]
	v_pk_mul_f32 v[174:175], v[140:141], v[92:93] op_sel_hi:[0,1]
	v_pk_mul_f32 v[176:177], v[140:141], v[90:91] op_sel_hi:[0,1]
	v_pk_mul_f32 v[170:171], v[140:141], v[94:95] op_sel_hi:[0,1]
	s_waitcnt vmcnt(0)
	v_mov_b32_e32 v188, v182
	v_mov_b32_e32 v189, v184
	v_mov_b32_e32 v184, v183
	v_pk_mul_f32 v[182:183], v[186:187], v[184:185]
	v_pk_mul_f32 v[186:187], v[186:187], v[188:189]
	v_pk_fma_f32 v[182:183], v[174:175], v[188:189], v[182:183] neg_lo:[0,0,1] neg_hi:[0,0,1]
	v_pk_fma_f32 v[174:175], v[174:175], v[184:185], v[186:187]
	v_mov_b32_e32 v185, v168
	v_mov_b32_e32 v168, v167
	v_mov_b32_e32 v184, v166
	v_pk_mul_f32 v[166:167], v[176:177], v[168:169]
	v_pk_mul_f32 v[176:177], v[176:177], v[184:185]
	v_pk_fma_f32 v[166:167], v[170:171], v[184:185], v[166:167] neg_lo:[0,0,1] neg_hi:[0,0,1]
	v_pk_fma_f32 v[168:169], v[170:171], v[168:169], v[176:177]
	v_cvt_pk_bf16_f32 v171, v166, v167
	v_lshlrev_b64 v[166:167], 6, v[160:161]
	v_lshl_add_u64 v[166:167], s[36:37], 0, v[166:167]
	v_cvt_pk_bf16_f32 v170, v182, v183
	v_lshl_add_u64 v[166:167], v[166:167], 0, v[164:165]
	global_store_dwordx2 v[166:167], v[170:171], off
	v_cvt_pk_bf16_f32 v170, v174, v175
	v_cvt_pk_bf16_f32 v171, v168, v169
	global_store_dwordx2 v[166:167], v[170:171], off offset:32
	v_pk_mul_f32 v[170:171], v[138:139], v[78:79] op_sel_hi:[0,1]
	v_pk_mul_f32 v[174:175], v[138:139], v[76:77] op_sel_hi:[0,1]
	v_pk_mul_f32 v[176:177], v[138:139], v[74:75] op_sel_hi:[0,1]
	v_pk_mul_f32 v[186:187], v[138:139], v[72:73] op_sel_hi:[0,1]
	v_lshlrev_b32_e32 v139, 7, v158
	v_and_b32_e32 v166, 0x7df80, v139
	v_mov_b32_e32 v167, v113
	v_lshl_add_u64 v[166:167], s[46:47], 0, v[166:167]
	v_lshl_add_u64 v[182:183], v[166:167], 0, v[112:113]
	global_load_dwordx4 v[166:169], v[182:183], off offset:16
	s_nop 0
	global_load_dwordx4 v[182:185], v[182:183], off
	v_lshlrev_b32_e32 v139, 7, v154
	s_waitcnt vmcnt(0)
	v_mov_b32_e32 v188, v182
	v_mov_b32_e32 v189, v184
	v_mov_b32_e32 v184, v183
	v_pk_mul_f32 v[182:183], v[186:187], v[184:185]
	v_pk_mul_f32 v[186:187], v[186:187], v[188:189]
	v_pk_fma_f32 v[182:183], v[174:175], v[188:189], v[182:183] neg_lo:[0,0,1] neg_hi:[0,0,1]
	v_pk_fma_f32 v[174:175], v[174:175], v[184:185], v[186:187]
	v_mov_b32_e32 v185, v168
	v_mov_b32_e32 v168, v167
	v_mov_b32_e32 v184, v166
	v_pk_mul_f32 v[166:167], v[176:177], v[168:169]
	v_pk_mul_f32 v[176:177], v[176:177], v[184:185]
	v_pk_fma_f32 v[166:167], v[170:171], v[184:185], v[166:167] neg_lo:[0,0,1] neg_hi:[0,0,1]
	v_pk_fma_f32 v[168:169], v[170:171], v[168:169], v[176:177]
	v_cvt_pk_bf16_f32 v171, v166, v167
	v_lshlrev_b64 v[166:167], 6, v[158:159]
	v_lshl_add_u64 v[166:167], s[36:37], 0, v[166:167]
	v_cvt_pk_bf16_f32 v170, v182, v183
	v_lshl_add_u64 v[166:167], v[166:167], 0, v[164:165]
	global_store_dwordx2 v[166:167], v[170:171], off
	v_cvt_pk_bf16_f32 v170, v174, v175
	v_cvt_pk_bf16_f32 v171, v168, v169
	global_store_dwordx2 v[166:167], v[170:171], off offset:32
	v_and_b32_e32 v166, 0x7e780, v139
	v_mov_b32_e32 v167, v113
	v_lshl_add_u64 v[166:167], s[46:47], 0, v[166:167]
	v_lshl_add_u64 v[182:183], v[166:167], 0, v[112:113]
	global_load_dwordx4 v[166:169], v[182:183], off offset:16
	s_nop 0
	global_load_dwordx4 v[182:185], v[182:183], off
	v_pk_mul_f32 v[186:187], v[136:137], v[56:57] op_sel_hi:[0,1]
	v_pk_mul_f32 v[174:175], v[136:137], v[60:61] op_sel_hi:[0,1]
	v_pk_mul_f32 v[176:177], v[136:137], v[58:59] op_sel_hi:[0,1]
	v_pk_mul_f32 v[170:171], v[136:137], v[62:63] op_sel_hi:[0,1]
	v_lshlrev_b32_e32 v139, 7, v152
	s_waitcnt vmcnt(0)
	v_mov_b32_e32 v188, v182
	v_mov_b32_e32 v189, v184
	v_mov_b32_e32 v184, v183
	v_pk_mul_f32 v[182:183], v[186:187], v[184:185]
	v_pk_mul_f32 v[186:187], v[186:187], v[188:189]
	v_pk_fma_f32 v[182:183], v[174:175], v[188:189], v[182:183] neg_lo:[0,0,1] neg_hi:[0,0,1]
	v_pk_fma_f32 v[174:175], v[174:175], v[184:185], v[186:187]
	v_mov_b32_e32 v185, v168
	v_mov_b32_e32 v168, v167
	v_mov_b32_e32 v184, v166
	v_pk_mul_f32 v[166:167], v[176:177], v[168:169]
	v_pk_mul_f32 v[176:177], v[176:177], v[184:185]
	v_pk_fma_f32 v[166:167], v[170:171], v[184:185], v[166:167] neg_lo:[0,0,1] neg_hi:[0,0,1]
	v_pk_fma_f32 v[168:169], v[170:171], v[168:169], v[176:177]
	v_cvt_pk_bf16_f32 v171, v166, v167
	v_lshlrev_b64 v[166:167], 6, v[154:155]
	v_lshl_add_u64 v[166:167], s[36:37], 0, v[166:167]
	v_cvt_pk_bf16_f32 v170, v182, v183
	v_lshl_add_u64 v[166:167], v[166:167], 0, v[164:165]
	global_store_dwordx2 v[166:167], v[170:171], off
	v_cvt_pk_bf16_f32 v170, v174, v175
	v_cvt_pk_bf16_f32 v171, v168, v169
	global_store_dwordx2 v[166:167], v[170:171], off offset:32
	v_and_b32_e32 v166, 0x7ef80, v139
	v_mov_b32_e32 v167, v113
	v_lshl_add_u64 v[166:167], s[46:47], 0, v[166:167]
	v_lshl_add_u64 v[182:183], v[166:167], 0, v[112:113]
	global_load_dwordx4 v[166:169], v[182:183], off offset:16
	s_nop 0
	global_load_dwordx4 v[182:185], v[182:183], off
	v_pk_mul_f32 v[186:187], v[134:135], v[40:41] op_sel_hi:[0,1]
	v_pk_mul_f32 v[174:175], v[134:135], v[44:45] op_sel_hi:[0,1]
	v_pk_mul_f32 v[176:177], v[134:135], v[42:43] op_sel_hi:[0,1]
	v_pk_mul_f32 v[170:171], v[134:135], v[46:47] op_sel_hi:[0,1]
	v_lshlrev_b32_e32 v139, 7, v150
	s_waitcnt vmcnt(0)
	v_mov_b32_e32 v188, v182
	v_mov_b32_e32 v189, v184
	v_mov_b32_e32 v184, v183
	v_pk_mul_f32 v[182:183], v[186:187], v[184:185]
	v_pk_mul_f32 v[186:187], v[186:187], v[188:189]
	v_pk_fma_f32 v[182:183], v[174:175], v[188:189], v[182:183] neg_lo:[0,0,1] neg_hi:[0,0,1]
	v_pk_fma_f32 v[174:175], v[174:175], v[184:185], v[186:187]
	v_mov_b32_e32 v185, v168
	v_mov_b32_e32 v168, v167
	v_mov_b32_e32 v184, v166
	v_pk_mul_f32 v[166:167], v[176:177], v[168:169]
	v_pk_mul_f32 v[176:177], v[176:177], v[184:185]
	v_pk_fma_f32 v[166:167], v[170:171], v[184:185], v[166:167] neg_lo:[0,0,1] neg_hi:[0,0,1]
	v_pk_fma_f32 v[168:169], v[170:171], v[168:169], v[176:177]
	v_cvt_pk_bf16_f32 v171, v166, v167
	v_lshlrev_b64 v[166:167], 6, v[152:153]
	v_lshl_add_u64 v[166:167], s[36:37], 0, v[166:167]
	v_cvt_pk_bf16_f32 v170, v182, v183
	v_lshl_add_u64 v[166:167], v[166:167], 0, v[164:165]
	global_store_dwordx2 v[166:167], v[170:171], off
	v_cvt_pk_bf16_f32 v170, v174, v175
	v_cvt_pk_bf16_f32 v171, v168, v169
	global_store_dwordx2 v[166:167], v[170:171], off offset:32
	v_and_b32_e32 v166, 0x7f780, v139
	v_mov_b32_e32 v167, v113
	v_lshl_add_u64 v[166:167], s[46:47], 0, v[166:167]
	v_lshl_add_u64 v[182:183], v[166:167], 0, v[112:113]
	global_load_dwordx4 v[166:169], v[182:183], off offset:16
	s_nop 0
	global_load_dwordx4 v[182:185], v[182:183], off
	v_pk_mul_f32 v[186:187], v[132:133], v[24:25] op_sel_hi:[0,1]
	v_pk_mul_f32 v[174:175], v[132:133], v[28:29] op_sel_hi:[0,1]
	v_pk_mul_f32 v[176:177], v[132:133], v[26:27] op_sel_hi:[0,1]
	v_pk_mul_f32 v[170:171], v[132:133], v[30:31] op_sel_hi:[0,1]
	v_lshlrev_b32_e32 v139, 7, v148
	s_waitcnt vmcnt(0)
	v_mov_b32_e32 v188, v182
	v_mov_b32_e32 v189, v184
	v_mov_b32_e32 v184, v183
	v_pk_mul_f32 v[182:183], v[186:187], v[184:185]
	v_pk_mul_f32 v[186:187], v[186:187], v[188:189]
	v_pk_fma_f32 v[182:183], v[174:175], v[188:189], v[182:183] neg_lo:[0,0,1] neg_hi:[0,0,1]
	v_pk_fma_f32 v[174:175], v[174:175], v[184:185], v[186:187]
	v_mov_b32_e32 v185, v168
	v_mov_b32_e32 v168, v167
	v_mov_b32_e32 v184, v166
	v_pk_mul_f32 v[166:167], v[176:177], v[168:169]
	v_pk_mul_f32 v[176:177], v[176:177], v[184:185]
	v_pk_fma_f32 v[166:167], v[170:171], v[184:185], v[166:167] neg_lo:[0,0,1] neg_hi:[0,0,1]
	v_pk_fma_f32 v[168:169], v[170:171], v[168:169], v[176:177]
	v_cvt_pk_bf16_f32 v171, v166, v167
	v_lshlrev_b64 v[166:167], 6, v[150:151]
	v_lshl_add_u64 v[166:167], s[36:37], 0, v[166:167]
	v_cvt_pk_bf16_f32 v170, v182, v183
	v_lshl_add_u64 v[166:167], v[166:167], 0, v[164:165]
	global_store_dwordx2 v[166:167], v[170:171], off
	v_cvt_pk_bf16_f32 v170, v174, v175
	v_cvt_pk_bf16_f32 v171, v168, v169
	global_store_dwordx2 v[166:167], v[170:171], off offset:32
	v_and_b32_e32 v166, 0x7ff80, v139
	v_mov_b32_e32 v167, v113
	v_lshl_add_u64 v[166:167], s[46:47], 0, v[166:167]
	v_lshl_add_u64 v[182:183], v[166:167], 0, v[112:113]
	global_load_dwordx4 v[166:169], v[182:183], off offset:16
	s_nop 0
	global_load_dwordx4 v[182:185], v[182:183], off
	v_pk_mul_f32 v[186:187], v[130:131], v[8:9] op_sel_hi:[0,1]
	v_pk_mul_f32 v[174:175], v[130:131], v[12:13] op_sel_hi:[0,1]
	v_pk_mul_f32 v[176:177], v[130:131], v[10:11] op_sel_hi:[0,1]
	v_pk_mul_f32 v[170:171], v[130:131], v[14:15] op_sel_hi:[0,1]
	s_waitcnt vmcnt(0)
	v_mov_b32_e32 v188, v182
	v_mov_b32_e32 v189, v184
	v_mov_b32_e32 v184, v183
	v_pk_mul_f32 v[182:183], v[186:187], v[184:185]
	v_pk_mul_f32 v[186:187], v[186:187], v[188:189]
	v_pk_fma_f32 v[182:183], v[174:175], v[188:189], v[182:183] neg_lo:[0,0,1] neg_hi:[0,0,1]
	v_pk_fma_f32 v[174:175], v[174:175], v[184:185], v[186:187]
	v_mov_b32_e32 v185, v168
	v_mov_b32_e32 v168, v167
	v_mov_b32_e32 v184, v166
	v_pk_mul_f32 v[166:167], v[176:177], v[168:169]
	v_pk_mul_f32 v[176:177], v[176:177], v[184:185]
	v_pk_fma_f32 v[166:167], v[170:171], v[184:185], v[166:167] neg_lo:[0,0,1] neg_hi:[0,0,1]
	v_pk_fma_f32 v[168:169], v[170:171], v[168:169], v[176:177]
	v_cvt_pk_bf16_f32 v171, v166, v167
	v_lshlrev_b64 v[166:167], 6, v[148:149]
	v_lshl_add_u64 v[166:167], s[36:37], 0, v[166:167]
	v_cvt_pk_bf16_f32 v170, v182, v183
	v_lshl_add_u64 v[164:165], v[166:167], 0, v[164:165]
	v_cvt_pk_bf16_f32 v166, v174, v175
	v_cvt_pk_bf16_f32 v167, v168, v169
	global_store_dwordx2 v[164:165], v[170:171], off
	global_store_dwordx2 v[164:165], v[166:167], off offset:32

.Lgsk1_loop:
	s_add_i32 s9, s8, 0xfffe8000
	s_and_b32 s10, s8, 0x18000
	s_and_b32 s9, s9, 0x18000
	s_add_i32 s10, s7, s10
	v_add_u32_e32 v112, s9, v139
	v_or_b32_e32 v141, s9, v140
	s_add_i32 s18, s10, 0x400
	s_add_i32 s11, s10, 0x800
	s_add_i32 s9, s10, 0xc00
	s_add_i32 s8, s8, 0x8000
	s_cmp_eq_u32 s8, 0x100000
	s_waitcnt vmcnt(8) lgkmcnt(0)
	s_barrier
	v_mfma_f32_16x16x32_bf16 v[60:63], v[142:145], v[232:235], v[60:63]
	ds_read_b128 v[162:165], v112
	ds_read_b128 v[166:169], v112 offset:1024
	v_mfma_f32_16x16x32_bf16 v[44:47], v[142:145], v[236:239], v[44:47]
	ds_read_b128 v[174:177], v112 offset:2048
	ds_read_b128 v[182:185], v112 offset:3072
	v_mfma_f32_16x16x32_bf16 v[28:31], v[142:145], v[240:243], v[28:31]
	s_mov_b32 m0, s10
	v_mfma_f32_16x16x32_bf16 v[12:15], v[142:145], v[244:247], v[12:15]
	global_load_lds_dwordx4 v[136:137], off
	v_lshl_add_u64 v[136:137], v[136:137], 0, 64
	v_mfma_f32_16x16x32_bf16 v[56:59], v[146:149], v[232:235], v[56:59]
	ds_read_b128 v[142:145], v141
	v_mfma_f32_16x16x32_bf16 v[40:43], v[146:149], v[236:239], v[40:43]
	v_mfma_f32_16x16x32_bf16 v[24:27], v[146:149], v[240:243], v[24:27]
	s_mov_b32 m0, s18
	v_mfma_f32_16x16x32_bf16 v[8:11], v[146:149], v[244:247], v[8:11]
	global_load_lds_dwordx4 v[134:135], off
	v_lshl_add_u64 v[134:135], v[134:135], 0, 64
	v_mfma_f32_16x16x32_bf16 v[52:55], v[150:153], v[232:235], v[52:55]
	ds_read_b128 v[146:149], v141 offset:1024
	v_mfma_f32_16x16x32_bf16 v[36:39], v[150:153], v[236:239], v[36:39]
	v_mfma_f32_16x16x32_bf16 v[20:23], v[150:153], v[240:243], v[20:23]
	s_mov_b32 m0, s11
	v_mfma_f32_16x16x32_bf16 v[4:7], v[150:153], v[244:247], v[4:7]
	global_load_lds_dwordx4 v[132:133], off
	v_lshl_add_u64 v[132:133], v[132:133], 0, 64
	v_mfma_f32_16x16x32_bf16 v[48:51], v[158:161], v[232:235], v[48:51]
	ds_read_b128 v[150:153], v141 offset:2048
	v_mfma_f32_16x16x32_bf16 v[32:35], v[158:161], v[236:239], v[32:35]
	v_mfma_f32_16x16x32_bf16 v[16:19], v[158:161], v[240:243], v[16:19]
	s_mov_b32 m0, s9
	v_mfma_f32_16x16x32_bf16 v[0:3], v[158:161], v[244:247], v[0:3]
	global_load_lds_dwordx4 v[130:131], off
	v_lshl_add_u64 v[130:131], v[130:131], 0, 64
	s_waitcnt lgkmcnt(2)
	v_mfma_f32_16x16x32_bf16 v[126:129], v[142:145], v[162:165], v[126:129]
	ds_read_b128 v[158:161], v141 offset:3072
	v_mfma_f32_16x16x32_bf16 v[108:111], v[142:145], v[166:169], v[108:111]
	ds_read_b128 v[232:235], v112 offset:4096
	ds_read_b128 v[236:239], v112 offset:5120
	v_mfma_f32_16x16x32_bf16 v[92:95], v[142:145], v[174:177], v[92:95]
	ds_read_b128 v[240:243], v112 offset:6144
	ds_read_b128 v[244:247], v112 offset:7168
	v_mfma_f32_16x16x32_bf16 v[76:79], v[142:145], v[182:185], v[76:79]
	s_waitcnt lgkmcnt(6)
	v_mfma_f32_16x16x32_bf16 v[122:125], v[146:149], v[162:165], v[122:125]
	v_mfma_f32_16x16x32_bf16 v[104:107], v[146:149], v[166:169], v[104:107]
	v_mfma_f32_16x16x32_bf16 v[88:91], v[146:149], v[174:177], v[88:91]
	v_mfma_f32_16x16x32_bf16 v[72:75], v[146:149], v[182:185], v[72:75]
	s_waitcnt lgkmcnt(5)
	v_mfma_f32_16x16x32_bf16 v[118:121], v[150:153], v[162:165], v[118:121]
	v_mfma_f32_16x16x32_bf16 v[100:103], v[150:153], v[166:169], v[100:103]
	v_mfma_f32_16x16x32_bf16 v[84:87], v[150:153], v[174:177], v[84:87]
	v_mfma_f32_16x16x32_bf16 v[68:71], v[150:153], v[182:185], v[68:71]
	s_waitcnt lgkmcnt(4)
	v_mfma_f32_16x16x32_bf16 v[114:117], v[158:161], v[162:165], v[114:117]
	v_mfma_f32_16x16x32_bf16 v[96:99], v[158:161], v[166:169], v[96:99]
	v_mfma_f32_16x16x32_bf16 v[80:83], v[158:161], v[174:177], v[80:83]
	v_mfma_f32_16x16x32_bf16 v[64:67], v[158:161], v[182:185], v[64:67]
	s_cbranch_scc0 .Lgsk1_loop
	s_waitcnt lgkmcnt(0)
	v_mfma_f32_16x16x32_bf16 v[60:63], v[142:145], v[232:235], v[60:63]
	v_mfma_f32_16x16x32_bf16 v[44:47], v[142:145], v[236:239], v[44:47]
	v_mfma_f32_16x16x32_bf16 v[28:31], v[142:145], v[240:243], v[28:31]
	v_mfma_f32_16x16x32_bf16 v[12:15], v[142:145], v[244:247], v[12:15]
	v_mfma_f32_16x16x32_bf16 v[56:59], v[146:149], v[232:235], v[56:59]
	v_mfma_f32_16x16x32_bf16 v[40:43], v[146:149], v[236:239], v[40:43]
	v_mfma_f32_16x16x32_bf16 v[24:27], v[146:149], v[240:243], v[24:27]
	v_mfma_f32_16x16x32_bf16 v[8:11], v[146:149], v[244:247], v[8:11]
	v_mfma_f32_16x16x32_bf16 v[52:55], v[150:153], v[232:235], v[52:55]
	v_mfma_f32_16x16x32_bf16 v[36:39], v[150:153], v[236:239], v[36:39]
	v_mfma_f32_16x16x32_bf16 v[20:23], v[150:153], v[240:243], v[20:23]
	v_mfma_f32_16x16x32_bf16 v[4:7], v[150:153], v[244:247], v[4:7]
	v_mfma_f32_16x16x32_bf16 v[48:51], v[158:161], v[232:235], v[48:51]
	v_mfma_f32_16x16x32_bf16 v[32:35], v[158:161], v[236:239], v[32:35]
	v_mfma_f32_16x16x32_bf16 v[16:19], v[158:161], v[240:243], v[16:19]
	v_mfma_f32_16x16x32_bf16 v[0:3], v[158:161], v[244:247], v[0:3]
	s_waitcnt vmcnt(8)
	s_barrier
	v_add_u32_e32 v112, 0x8000, v139
	v_or_b32_e32 v141, 0x8000, v140
	ds_read_b128 v[130:133], v141
	ds_read_b128 v[134:137], v141 offset:1024
	ds_read_b128 v[142:145], v141 offset:2048
	ds_read_b128 v[146:149], v141 offset:3072
	ds_read_b128 v[150:153], v112
	ds_read_b128 v[158:161], v112 offset:1024
	ds_read_b128 v[162:165], v112 offset:2048
	ds_read_b128 v[166:169], v112 offset:3072
	v_add_u32_e32 v141, 0x10000, v139
	s_waitcnt lgkmcnt(0)
	v_or_b32_e32 v154, 0x10000, v140
	v_mfma_f32_16x16x32_bf16 v[126:129], v[130:133], v[150:153], v[126:129]
	v_add_u32_e32 v139, 0x18000, v139
	s_lshl_b32 s8, s6, 8
	v_and_b32_e32 v170, 15, v138
	v_mfma_f32_16x16x32_bf16 v[122:125], v[134:137], v[150:153], v[122:125]
	s_and_b32 s18, s8, 0xffffc000
	s_ashr_i32 s7, s6, 1
	s_and_b32 s7, s7, 0xffffff80
	v_mfma_f32_16x16x32_bf16 v[118:121], v[142:145], v[150:153], v[118:121]
	s_and_b32 s6, s6, 0xc0
	s_add_i32 s8, s4, s7
	s_or_b32 s4, s5, s6
	v_mfma_f32_16x16x32_bf16 v[114:117], v[146:149], v[150:153], v[114:117]
	s_ashr_i32 s10, s4, 6
	s_ashr_i32 s11, s10, 31
	v_mfma_f32_16x16x32_bf16 v[108:111], v[130:133], v[158:161], v[108:111]
	v_mfma_f32_16x16x32_bf16 v[104:107], v[134:137], v[158:161], v[104:107]
	v_mfma_f32_16x16x32_bf16 v[100:103], v[142:145], v[158:161], v[100:103]
	v_mfma_f32_16x16x32_bf16 v[96:99], v[146:149], v[158:161], v[96:99]
	v_mfma_f32_16x16x32_bf16 v[92:95], v[130:133], v[162:165], v[92:95]
	v_mfma_f32_16x16x32_bf16 v[88:91], v[134:137], v[162:165], v[88:91]
	v_mfma_f32_16x16x32_bf16 v[84:87], v[142:145], v[162:165], v[84:87]
	v_mfma_f32_16x16x32_bf16 v[80:83], v[146:149], v[162:165], v[80:83]
	v_mfma_f32_16x16x32_bf16 v[76:79], v[130:133], v[166:169], v[76:79]
	v_mfma_f32_16x16x32_bf16 v[72:75], v[134:137], v[166:169], v[72:75]
	v_mfma_f32_16x16x32_bf16 v[68:71], v[142:145], v[166:169], v[68:71]
	v_mfma_f32_16x16x32_bf16 v[64:67], v[146:149], v[166:169], v[64:67]
	ds_read_b128 v[150:153], v112 offset:4096
	ds_read_b128 v[158:161], v112 offset:5120
	ds_read_b128 v[162:165], v112 offset:6144
	ds_read_b128 v[166:169], v112 offset:7168
	s_waitcnt lgkmcnt(0)
	s_waitcnt vmcnt(4)
	s_barrier
	v_mfma_f32_16x16x32_bf16 v[60:63], v[130:133], v[150:153], v[60:63]
	v_and_b32_e32 v112, 63, v138
	v_mfma_f32_16x16x32_bf16 v[56:59], v[134:137], v[150:153], v[56:59]
	v_mfma_f32_16x16x32_bf16 v[52:55], v[142:145], v[150:153], v[52:55]
	v_mfma_f32_16x16x32_bf16 v[48:51], v[146:149], v[150:153], v[48:51]
	v_mfma_f32_16x16x32_bf16 v[44:47], v[130:133], v[158:161], v[44:47]
	v_mfma_f32_16x16x32_bf16 v[40:43], v[134:137], v[158:161], v[40:43]
	v_mfma_f32_16x16x32_bf16 v[36:39], v[142:145], v[158:161], v[36:39]
	v_mfma_f32_16x16x32_bf16 v[32:35], v[146:149], v[158:161], v[32:35]
	v_mfma_f32_16x16x32_bf16 v[28:31], v[130:133], v[162:165], v[28:31]
	v_mfma_f32_16x16x32_bf16 v[24:27], v[134:137], v[162:165], v[24:27]
	v_mfma_f32_16x16x32_bf16 v[20:23], v[142:145], v[162:165], v[20:23]
	v_mfma_f32_16x16x32_bf16 v[16:19], v[146:149], v[162:165], v[16:19]
	v_mfma_f32_16x16x32_bf16 v[12:15], v[130:133], v[166:169], v[12:15]
	v_mfma_f32_16x16x32_bf16 v[8:11], v[134:137], v[166:169], v[8:11]
	v_mfma_f32_16x16x32_bf16 v[4:7], v[142:145], v[166:169], v[4:7]
	v_mfma_f32_16x16x32_bf16 v[0:3], v[146:149], v[166:169], v[0:3]
	ds_read_b128 v[130:133], v154
	ds_read_b128 v[134:137], v154 offset:1024
	ds_read_b128 v[142:145], v154 offset:2048
	ds_read_b128 v[146:149], v154 offset:3072
	ds_read_b128 v[150:153], v141
	ds_read_b128 v[158:161], v141 offset:1024
	ds_read_b128 v[162:165], v141 offset:2048
	ds_read_b128 v[166:169], v141 offset:3072
	s_nop 0
	s_waitcnt lgkmcnt(0)
	s_nop 0
	v_mfma_f32_16x16x32_bf16 v[126:129], v[130:133], v[150:153], v[126:129]
	v_mfma_f32_16x16x32_bf16 v[122:125], v[134:137], v[150:153], v[122:125]
	v_mfma_f32_16x16x32_bf16 v[118:121], v[142:145], v[150:153], v[118:121]
	v_mfma_f32_16x16x32_bf16 v[114:117], v[146:149], v[150:153], v[114:117]
	v_mfma_f32_16x16x32_bf16 v[108:111], v[130:133], v[158:161], v[108:111]
	v_mfma_f32_16x16x32_bf16 v[104:107], v[134:137], v[158:161], v[104:107]
	v_mfma_f32_16x16x32_bf16 v[100:103], v[142:145], v[158:161], v[100:103]
	v_mfma_f32_16x16x32_bf16 v[150:153], v[146:149], v[158:161], v[96:99]
	v_mfma_f32_16x16x32_bf16 v[92:95], v[130:133], v[162:165], v[92:95]
	v_mfma_f32_16x16x32_bf16 v[88:91], v[134:137], v[162:165], v[88:91]
	v_mfma_f32_16x16x32_bf16 v[84:87], v[142:145], v[162:165], v[84:87]
	v_mfma_f32_16x16x32_bf16 v[80:83], v[146:149], v[162:165], v[80:83]
	v_mfma_f32_16x16x32_bf16 v[76:79], v[130:133], v[166:169], v[76:79]
	v_mfma_f32_16x16x32_bf16 v[72:75], v[134:137], v[166:169], v[72:75]
	v_mfma_f32_16x16x32_bf16 v[68:71], v[142:145], v[166:169], v[68:71]
	v_mfma_f32_16x16x32_bf16 v[64:67], v[146:149], v[166:169], v[64:67]
	ds_read_b128 v[96:99], v141 offset:4096
	ds_read_b128 v[158:161], v141 offset:5120
	ds_read_b128 v[162:165], v141 offset:6144
	ds_read_b128 v[166:169], v141 offset:7168
	s_waitcnt lgkmcnt(0)
	s_waitcnt vmcnt(0)
	s_barrier
	v_mfma_f32_16x16x32_bf16 v[60:63], v[130:133], v[96:99], v[60:63]
	v_mfma_f32_16x16x32_bf16 v[56:59], v[134:137], v[96:99], v[56:59]
	v_mfma_f32_16x16x32_bf16 v[52:55], v[142:145], v[96:99], v[52:55]
	v_mfma_f32_16x16x32_bf16 v[48:51], v[146:149], v[96:99], v[48:51]
	v_mfma_f32_16x16x32_bf16 v[44:47], v[130:133], v[158:161], v[44:47]
	v_mfma_f32_16x16x32_bf16 v[40:43], v[134:137], v[158:161], v[40:43]
	v_mfma_f32_16x16x32_bf16 v[36:39], v[142:145], v[158:161], v[36:39]
	v_mfma_f32_16x16x32_bf16 v[32:35], v[146:149], v[158:161], v[32:35]
	v_mfma_f32_16x16x32_bf16 v[28:31], v[130:133], v[162:165], v[28:31]
	v_mfma_f32_16x16x32_bf16 v[24:27], v[134:137], v[162:165], v[24:27]
	v_mfma_f32_16x16x32_bf16 v[20:23], v[142:145], v[162:165], v[20:23]
	v_mfma_f32_16x16x32_bf16 v[16:19], v[146:149], v[162:165], v[16:19]
	v_mfma_f32_16x16x32_bf16 v[12:15], v[130:133], v[166:169], v[12:15]
	v_mfma_f32_16x16x32_bf16 v[8:11], v[134:137], v[166:169], v[8:11]
	v_mfma_f32_16x16x32_bf16 v[4:7], v[142:145], v[166:169], v[4:7]
	v_mfma_f32_16x16x32_bf16 v[0:3], v[146:149], v[166:169], v[0:3]
	v_or_b32_e32 v148, 0x18000, v140
	ds_read_b128 v[130:133], v148
	ds_read_b128 v[134:137], v148 offset:1024
	ds_read_b128 v[140:143], v148 offset:2048
	ds_read_b128 v[144:147], v148 offset:3072
	ds_read_b128 v[96:99], v139
	ds_read_b128 v[158:161], v139 offset:1024
	ds_read_b128 v[162:165], v139 offset:2048
	ds_read_b128 v[166:169], v139 offset:3072
	s_nop 0
	s_waitcnt lgkmcnt(0)
	s_nop 0
	v_mfma_f32_16x16x32_bf16 v[126:129], v[130:133], v[96:99], v[126:129]
	v_mfma_f32_16x16x32_bf16 v[174:177], v[134:137], v[96:99], v[122:125]
	v_mfma_f32_16x16x32_bf16 v[182:185], v[140:143], v[96:99], v[118:121]
	v_mfma_f32_16x16x32_bf16 v[114:117], v[144:147], v[96:99], v[114:117]
	v_mfma_f32_16x16x32_bf16 v[96:99], v[140:143], v[158:161], v[100:103]
	v_mfma_f32_16x16x32_bf16 v[100:103], v[144:147], v[158:161], v[150:153]
	ds_read_b128 v[118:121], v139 offset:4096
	ds_read_b128 v[122:125], v139 offset:5120
	ds_read_b128 v[148:151], v139 offset:6144
	ds_read_b128 v[152:155], v139 offset:7168
	s_waitcnt lgkmcnt(0)
	s_barrier
	v_mfma_f32_16x16x32_bf16 v[60:63], v[130:133], v[118:121], v[60:63]
	v_mfma_f32_16x16x32_bf16 v[56:59], v[134:137], v[118:121], v[56:59]
	v_mfma_f32_16x16x32_bf16 v[52:55], v[140:143], v[118:121], v[52:55]
	v_mfma_f32_16x16x32_bf16 v[48:51], v[144:147], v[118:121], v[48:51]
	v_bfe_u32 v119, v138, 5, 1
	v_lshrrev_b32_e32 v121, 1, v138
	v_lshlrev_b32_e32 v118, 7, v170
	v_mfma_f32_16x16x32_bf16 v[44:47], v[130:133], v[122:125], v[44:47]
	v_and_b32_e32 v121, 8, v121
	v_and_b32_e32 v120, 7, v138
	v_mfma_f32_16x16x32_bf16 v[40:43], v[134:137], v[122:125], v[40:43]
	v_mfma_f32_16x16x32_bf16 v[36:39], v[140:143], v[122:125], v[36:39]
	v_mfma_f32_16x16x32_bf16 v[32:35], v[144:147], v[122:125], v[32:35]
	v_mul_f32_e32 v125, v127, v127
	v_bitop3_b32 v124, v119, v138, 7 bitop3:0x78
	v_or3_b32 v123, s18, v118, v121
	v_fmac_f32_e32 v125, v126, v126
	v_lshlrev_b32_e32 v124, 4, v124
	v_fmac_f32_e32 v125, v128, v128
	v_cvt_pk_bf16_f32 v126, v126, v127
	v_cvt_pk_bf16_f32 v127, v128, v129
	v_or_b32_e32 v128, v123, v124
	s_waitcnt vmcnt(0)
	ds_write_b64 v128, v[126:127]
	v_mul_f32_e32 v126, v175, v175
	v_fmac_f32_e32 v126, v174, v174
	v_fmac_f32_e32 v126, v176, v176
	v_fmac_f32_e32 v125, v129, v129
	v_fmac_f32_e32 v126, v177, v177
	v_add_f32_e32 v125, v125, v126
	v_bitop3_b32 v126, v119, v120, 2 bitop3:0x36
	v_lshlrev_b32_e32 v126, 4, v126
	v_cvt_pk_bf16_f32 v128, v174, v175
	v_cvt_pk_bf16_f32 v129, v176, v177
	v_or_b32_e32 v127, v123, v126
	ds_write_b64 v127, v[128:129]
	v_mul_f32_e32 v127, v183, v183
	v_fmac_f32_e32 v127, v182, v182
	v_fmac_f32_e32 v127, v184, v184
	v_fmac_f32_e32 v127, v185, v185
	v_add_f32_e32 v127, v125, v127
	v_bitop3_b32 v125, v119, v120, 4 bitop3:0x36
	v_lshlrev_b32_e32 v125, 4, v125
	v_mfma_f32_16x16x32_bf16 v[108:111], v[130:133], v[158:161], v[108:111]
	v_cvt_pk_bf16_f32 v128, v182, v183
	v_cvt_pk_bf16_f32 v129, v184, v185
	v_and_b32_e32 v121, 64, v172
	v_mfma_f32_16x16x32_bf16 v[92:95], v[130:133], v[162:165], v[92:95]
	v_xor_b32_e32 v118, 16, v172
	v_add_u32_e32 v122, 64, v121
	v_cmp_lt_i32_e32 vcc, v118, v122
	v_mfma_f32_16x16x32_bf16 v[76:79], v[130:133], v[166:169], v[76:79]
	s_nop 0
	v_cndmask_b32_e32 v118, v172, v118, vcc
	v_lshlrev_b32_e32 v121, 2, v118
	v_mfma_f32_16x16x32_bf16 v[28:31], v[130:133], v[148:151], v[28:31]
	v_xor_b32_e32 v118, 32, v172
	v_cmp_lt_i32_e32 vcc, v118, v122
	v_mfma_f32_16x16x32_bf16 v[12:15], v[130:133], v[152:155], v[12:15]
	v_or_b32_e32 v130, v123, v125
	ds_write_b64 v130, v[128:129]
	v_mul_f32_e32 v128, v115, v115
	v_fmac_f32_e32 v128, v114, v114
	v_fmac_f32_e32 v128, v116, v116
	v_fmac_f32_e32 v128, v117, v117
	v_add_f32_e32 v127, v127, v128
	v_cvt_pk_bf16_f32 v128, v114, v115
	v_bitop3_b32 v114, v119, v120, 6 bitop3:0x36
	v_lshlrev_b32_e32 v114, 4, v114
	v_cvt_pk_bf16_f32 v129, v116, v117
	v_or_b32_e32 v115, v123, v114
	ds_write_b64 v115, v[128:129]
	ds_bpermute_b32 v115, v121, v127
	v_cndmask_b32_e32 v118, v172, v118, vcc
	v_lshlrev_b32_e32 v122, 2, v118
	v_mfma_f32_16x16x32_bf16 v[104:107], v[134:137], v[158:161], v[104:107]
	v_cmp_gt_u32_e32 vcc, 16, v112
	s_waitcnt lgkmcnt(0)
	v_add_f32_e32 v115, v127, v115
	ds_bpermute_b32 v116, v122, v115
	v_mfma_f32_16x16x32_bf16 v[88:91], v[134:137], v[162:165], v[88:91]
	v_or_b32_e32 v118, s8, v170
	v_mfma_f32_16x16x32_bf16 v[84:87], v[140:143], v[162:165], v[84:87]
	v_mfma_f32_16x16x32_bf16 v[80:83], v[144:147], v[162:165], v[80:83]
	v_mfma_f32_16x16x32_bf16 v[72:75], v[134:137], v[166:169], v[72:75]
	v_mfma_f32_16x16x32_bf16 v[68:71], v[140:143], v[166:169], v[68:71]
	v_mfma_f32_16x16x32_bf16 v[64:67], v[144:147], v[166:169], v[64:67]
	v_mfma_f32_16x16x32_bf16 v[24:27], v[134:137], v[148:151], v[24:27]
	v_mfma_f32_16x16x32_bf16 v[20:23], v[140:143], v[148:151], v[20:23]
	v_mfma_f32_16x16x32_bf16 v[16:19], v[144:147], v[148:151], v[16:19]
	v_mfma_f32_16x16x32_bf16 v[8:11], v[134:137], v[152:155], v[8:11]
	v_mfma_f32_16x16x32_bf16 v[4:7], v[140:143], v[152:155], v[4:7]
	v_mfma_f32_16x16x32_bf16 v[0:3], v[144:147], v[152:155], v[0:3]
	s_and_saveexec_b64 s[6:7], vcc
	s_cbranch_execz .LBB0_545
	v_ashrrev_i32_e32 v119, 31, v118
	s_waitcnt lgkmcnt(0)
	v_add_f32_e32 v115, v115, v116
	v_lshlrev_b64 v[116:117], 6, v[118:119]
	v_lshl_add_u64 v[116:117], s[44:45], 0, v[116:117]
	v_lshl_add_u64 v[116:117], s[10:11], 2, v[116:117]
	global_store_dword v[116:117], v115, off

.Lgsk2_loop:
	s_add_i32 s8, s5, 0xfffe8000
	s_and_b32 s9, s5, 0x18000
	s_and_b32 s8, s8, 0x18000
	s_add_i32 s9, s4, s9
	v_add_u32_e32 v128, s8, v160
	v_or_b32_e32 v170, s8, v161
	s_add_i32 s11, s9, 0x400
	s_add_i32 s10, s9, 0x800
	s_add_i32 s8, s9, 0xc00
	s_add_i32 s5, s5, 0x8000
	s_cmp_eq_u32 s5, 0x100000
	s_waitcnt vmcnt(8) lgkmcnt(0)
	s_barrier
	v_mfma_f32_16x16x32_bf16 v[60:63], v[162:165], v[232:235], v[60:63]
	ds_read_b128 v[182:185], v128
	ds_read_b128 v[186:189], v128 offset:1024
	v_mfma_f32_16x16x32_bf16 v[44:47], v[162:165], v[236:239], v[44:47]
	ds_read_b128 v[190:193], v128 offset:2048
	ds_read_b128 v[194:197], v128 offset:3072
	v_mfma_f32_16x16x32_bf16 v[28:31], v[162:165], v[240:243], v[28:31]
	s_mov_b32 m0, s9
	v_mfma_f32_16x16x32_bf16 v[12:15], v[162:165], v[244:247], v[12:15]
	global_load_lds_dwordx4 v[136:137], off
	v_lshl_add_u64 v[136:137], v[136:137], 0, 64
	v_mfma_f32_16x16x32_bf16 v[56:59], v[166:169], v[232:235], v[56:59]
	ds_read_b128 v[162:165], v170
	v_mfma_f32_16x16x32_bf16 v[40:43], v[166:169], v[236:239], v[40:43]
	v_mfma_f32_16x16x32_bf16 v[24:27], v[166:169], v[240:243], v[24:27]
	s_mov_b32 m0, s11
	v_mfma_f32_16x16x32_bf16 v[8:11], v[166:169], v[244:247], v[8:11]
	global_load_lds_dwordx4 v[134:135], off
	v_lshl_add_u64 v[134:135], v[134:135], 0, 64
	v_mfma_f32_16x16x32_bf16 v[52:55], v[174:177], v[232:235], v[52:55]
	ds_read_b128 v[166:169], v170 offset:1024
	v_mfma_f32_16x16x32_bf16 v[36:39], v[174:177], v[236:239], v[36:39]
	v_mfma_f32_16x16x32_bf16 v[20:23], v[174:177], v[240:243], v[20:23]
	s_mov_b32 m0, s10
	v_mfma_f32_16x16x32_bf16 v[4:7], v[174:177], v[244:247], v[4:7]
	global_load_lds_dwordx4 v[132:133], off
	v_lshl_add_u64 v[132:133], v[132:133], 0, 64
	v_mfma_f32_16x16x32_bf16 v[48:51], v[178:181], v[232:235], v[48:51]
	ds_read_b128 v[174:177], v170 offset:2048
	v_mfma_f32_16x16x32_bf16 v[32:35], v[178:181], v[236:239], v[32:35]
	v_mfma_f32_16x16x32_bf16 v[16:19], v[178:181], v[240:243], v[16:19]
	s_mov_b32 m0, s8
	v_mfma_f32_16x16x32_bf16 v[0:3], v[178:181], v[244:247], v[0:3]
	global_load_lds_dwordx4 v[130:131], off
	v_lshl_add_u64 v[130:131], v[130:131], 0, 64
	s_waitcnt lgkmcnt(2)
	v_mfma_f32_16x16x32_bf16 v[124:127], v[162:165], v[182:185], v[124:127]
	ds_read_b128 v[178:181], v170 offset:3072
	v_mfma_f32_16x16x32_bf16 v[108:111], v[162:165], v[186:189], v[108:111]
	ds_read_b128 v[232:235], v128 offset:4096
	ds_read_b128 v[236:239], v128 offset:5120
	v_mfma_f32_16x16x32_bf16 v[92:95], v[162:165], v[190:193], v[92:95]
	ds_read_b128 v[240:243], v128 offset:6144
	ds_read_b128 v[244:247], v128 offset:7168
	v_mfma_f32_16x16x32_bf16 v[76:79], v[162:165], v[194:197], v[76:79]
	s_waitcnt lgkmcnt(6)
	v_mfma_f32_16x16x32_bf16 v[120:123], v[166:169], v[182:185], v[120:123]
	v_mfma_f32_16x16x32_bf16 v[104:107], v[166:169], v[186:189], v[104:107]
	v_mfma_f32_16x16x32_bf16 v[88:91], v[166:169], v[190:193], v[88:91]
	v_mfma_f32_16x16x32_bf16 v[72:75], v[166:169], v[194:197], v[72:75]
	s_waitcnt lgkmcnt(5)
	v_mfma_f32_16x16x32_bf16 v[116:119], v[174:177], v[182:185], v[116:119]
	v_mfma_f32_16x16x32_bf16 v[100:103], v[174:177], v[186:189], v[100:103]
	v_mfma_f32_16x16x32_bf16 v[84:87], v[174:177], v[190:193], v[84:87]
	v_mfma_f32_16x16x32_bf16 v[68:71], v[174:177], v[194:197], v[68:71]
	s_waitcnt lgkmcnt(4)
	v_mfma_f32_16x16x32_bf16 v[112:115], v[178:181], v[182:185], v[112:115]
	v_mfma_f32_16x16x32_bf16 v[96:99], v[178:181], v[186:189], v[96:99]
	v_mfma_f32_16x16x32_bf16 v[80:83], v[178:181], v[190:193], v[80:83]
	v_mfma_f32_16x16x32_bf16 v[64:67], v[178:181], v[194:197], v[64:67]
	s_cbranch_scc0 .Lgsk2_loop
	s_waitcnt lgkmcnt(0)
	v_mfma_f32_16x16x32_bf16 v[60:63], v[162:165], v[232:235], v[60:63]
	v_mfma_f32_16x16x32_bf16 v[44:47], v[162:165], v[236:239], v[44:47]
	v_mfma_f32_16x16x32_bf16 v[28:31], v[162:165], v[240:243], v[28:31]
	v_mfma_f32_16x16x32_bf16 v[12:15], v[162:165], v[244:247], v[12:15]
	v_mfma_f32_16x16x32_bf16 v[56:59], v[166:169], v[232:235], v[56:59]
	v_mfma_f32_16x16x32_bf16 v[40:43], v[166:169], v[236:239], v[40:43]
	v_mfma_f32_16x16x32_bf16 v[24:27], v[166:169], v[240:243], v[24:27]
	v_mfma_f32_16x16x32_bf16 v[8:11], v[166:169], v[244:247], v[8:11]
	v_mfma_f32_16x16x32_bf16 v[52:55], v[174:177], v[232:235], v[52:55]
	v_mfma_f32_16x16x32_bf16 v[36:39], v[174:177], v[236:239], v[36:39]
	v_mfma_f32_16x16x32_bf16 v[20:23], v[174:177], v[240:243], v[20:23]
	v_mfma_f32_16x16x32_bf16 v[4:7], v[174:177], v[244:247], v[4:7]
	v_mfma_f32_16x16x32_bf16 v[48:51], v[178:181], v[232:235], v[48:51]
	v_mfma_f32_16x16x32_bf16 v[32:35], v[178:181], v[236:239], v[32:35]
	v_mfma_f32_16x16x32_bf16 v[16:19], v[178:181], v[240:243], v[16:19]
	v_mfma_f32_16x16x32_bf16 v[0:3], v[178:181], v[244:247], v[0:3]
	s_waitcnt vmcnt(8)
	s_barrier
	v_add_u32_e32 v128, 0x8000, v160
	v_or_b32_e32 v170, 0x8000, v161
	ds_read_b128 v[130:133], v170
	ds_read_b128 v[134:137], v170 offset:1024
	ds_read_b128 v[162:165], v170 offset:2048
	ds_read_b128 v[166:169], v170 offset:3072
	ds_read_b128 v[174:177], v128
	ds_read_b128 v[178:181], v128 offset:1024
	ds_read_b128 v[182:185], v128 offset:2048
	ds_read_b128 v[186:189], v128 offset:3072
	v_or_b32_e32 v170, 0x10000, v161
	s_waitcnt lgkmcnt(0)
	v_or_b32_e32 v173, 0x18000, v161
	v_mfma_f32_16x16x32_bf16 v[124:127], v[130:133], v[174:177], v[124:127]
	s_cmp_eq_u32 s13, 2
	s_cselect_b64 s[8:9], -1, 0
	s_cmp_eq_u32 s13, 3
	v_mfma_f32_16x16x32_bf16 v[120:123], v[134:137], v[174:177], v[120:123]
	s_cselect_b64 s[4:5], -1, 0
	s_and_b64 vcc, exec, s[4:5]
	v_mfma_f32_16x16x32_bf16 v[116:119], v[162:165], v[174:177], v[116:119]
	v_mfma_f32_16x16x32_bf16 v[112:115], v[166:169], v[174:177], v[112:115]
	v_mfma_f32_16x16x32_bf16 v[108:111], v[130:133], v[178:181], v[108:111]
	v_mfma_f32_16x16x32_bf16 v[104:107], v[134:137], v[178:181], v[104:107]
	v_mfma_f32_16x16x32_bf16 v[100:103], v[162:165], v[178:181], v[100:103]
	v_mfma_f32_16x16x32_bf16 v[96:99], v[166:169], v[178:181], v[96:99]
	v_mfma_f32_16x16x32_bf16 v[92:95], v[130:133], v[182:185], v[92:95]
	v_mfma_f32_16x16x32_bf16 v[88:91], v[134:137], v[182:185], v[88:91]
	v_mfma_f32_16x16x32_bf16 v[84:87], v[162:165], v[182:185], v[84:87]
	v_mfma_f32_16x16x32_bf16 v[80:83], v[166:169], v[182:185], v[80:83]
	v_mfma_f32_16x16x32_bf16 v[76:79], v[130:133], v[186:189], v[76:79]
	v_mfma_f32_16x16x32_bf16 v[72:75], v[134:137], v[186:189], v[72:75]
	v_mfma_f32_16x16x32_bf16 v[68:71], v[162:165], v[186:189], v[68:71]
	v_mfma_f32_16x16x32_bf16 v[64:67], v[166:169], v[186:189], v[64:67]
	ds_read_b128 v[174:177], v128 offset:4096
	ds_read_b128 v[178:181], v128 offset:5120
	ds_read_b128 v[182:185], v128 offset:6144
	ds_read_b128 v[186:189], v128 offset:7168
	s_waitcnt lgkmcnt(0)
	s_waitcnt vmcnt(4)
	s_barrier
	v_mfma_f32_16x16x32_bf16 v[60:63], v[130:133], v[174:177], v[60:63]
	v_add_u32_e32 v128, 0x10000, v160
	v_mfma_f32_16x16x32_bf16 v[56:59], v[134:137], v[174:177], v[56:59]
	v_mfma_f32_16x16x32_bf16 v[52:55], v[162:165], v[174:177], v[52:55]
	v_mfma_f32_16x16x32_bf16 v[48:51], v[166:169], v[174:177], v[48:51]
	v_mfma_f32_16x16x32_bf16 v[44:47], v[130:133], v[178:181], v[44:47]
	v_mfma_f32_16x16x32_bf16 v[40:43], v[134:137], v[178:181], v[40:43]
	v_mfma_f32_16x16x32_bf16 v[36:39], v[162:165], v[178:181], v[36:39]
	v_mfma_f32_16x16x32_bf16 v[32:35], v[166:169], v[178:181], v[32:35]
	v_mfma_f32_16x16x32_bf16 v[28:31], v[130:133], v[182:185], v[28:31]
	v_mfma_f32_16x16x32_bf16 v[24:27], v[134:137], v[182:185], v[24:27]
	v_mfma_f32_16x16x32_bf16 v[20:23], v[162:165], v[182:185], v[20:23]
	v_mfma_f32_16x16x32_bf16 v[16:19], v[166:169], v[182:185], v[16:19]
	v_mfma_f32_16x16x32_bf16 v[12:15], v[130:133], v[186:189], v[12:15]
	v_mfma_f32_16x16x32_bf16 v[8:11], v[134:137], v[186:189], v[8:11]
	v_mfma_f32_16x16x32_bf16 v[4:7], v[162:165], v[186:189], v[4:7]
	v_mfma_f32_16x16x32_bf16 v[0:3], v[166:169], v[186:189], v[0:3]
	ds_read_b128 v[130:133], v170
	ds_read_b128 v[134:137], v170 offset:1024
	ds_read_b128 v[162:165], v170 offset:2048
	ds_read_b128 v[166:169], v170 offset:3072
	ds_read_b128 v[174:177], v128
	ds_read_b128 v[178:181], v128 offset:1024
	ds_read_b128 v[182:185], v128 offset:2048
	ds_read_b128 v[186:189], v128 offset:3072
	s_nop 0
	s_waitcnt lgkmcnt(0)
	s_nop 0
	v_mfma_f32_16x16x32_bf16 v[124:127], v[130:133], v[174:177], v[124:127]
	v_mfma_f32_16x16x32_bf16 v[120:123], v[134:137], v[174:177], v[120:123]
	v_mfma_f32_16x16x32_bf16 v[116:119], v[162:165], v[174:177], v[116:119]
	v_mfma_f32_16x16x32_bf16 v[112:115], v[166:169], v[174:177], v[112:115]
	v_mfma_f32_16x16x32_bf16 v[108:111], v[130:133], v[178:181], v[108:111]
	v_mfma_f32_16x16x32_bf16 v[104:107], v[134:137], v[178:181], v[104:107]
	v_mfma_f32_16x16x32_bf16 v[100:103], v[162:165], v[178:181], v[100:103]
	v_mfma_f32_16x16x32_bf16 v[96:99], v[166:169], v[178:181], v[96:99]
	v_mfma_f32_16x16x32_bf16 v[92:95], v[130:133], v[182:185], v[92:95]
	v_mfma_f32_16x16x32_bf16 v[88:91], v[134:137], v[182:185], v[88:91]
	v_mfma_f32_16x16x32_bf16 v[84:87], v[162:165], v[182:185], v[84:87]
	v_mfma_f32_16x16x32_bf16 v[80:83], v[166:169], v[182:185], v[80:83]
	v_mfma_f32_16x16x32_bf16 v[76:79], v[130:133], v[186:189], v[76:79]
	v_mfma_f32_16x16x32_bf16 v[72:75], v[134:137], v[186:189], v[72:75]
	v_mfma_f32_16x16x32_bf16 v[68:71], v[162:165], v[186:189], v[68:71]
	v_mfma_f32_16x16x32_bf16 v[64:67], v[166:169], v[186:189], v[64:67]
	ds_read_b128 v[174:177], v128 offset:4096
	ds_read_b128 v[178:181], v128 offset:5120
	ds_read_b128 v[182:185], v128 offset:6144
	ds_read_b128 v[186:189], v128 offset:7168
	s_waitcnt lgkmcnt(0)
	s_waitcnt vmcnt(0)
	s_barrier
	v_mfma_f32_16x16x32_bf16 v[60:63], v[130:133], v[174:177], v[60:63]
	v_add_u32_e32 v128, 0x18000, v160
	v_mfma_f32_16x16x32_bf16 v[56:59], v[134:137], v[174:177], v[56:59]
	v_mfma_f32_16x16x32_bf16 v[52:55], v[162:165], v[174:177], v[52:55]
	v_mfma_f32_16x16x32_bf16 v[48:51], v[166:169], v[174:177], v[48:51]
	v_mfma_f32_16x16x32_bf16 v[44:47], v[130:133], v[178:181], v[44:47]
	v_mfma_f32_16x16x32_bf16 v[40:43], v[134:137], v[178:181], v[40:43]
	v_mfma_f32_16x16x32_bf16 v[36:39], v[162:165], v[178:181], v[36:39]
	v_mfma_f32_16x16x32_bf16 v[32:35], v[166:169], v[178:181], v[32:35]
	v_mfma_f32_16x16x32_bf16 v[28:31], v[130:133], v[182:185], v[28:31]
	v_mfma_f32_16x16x32_bf16 v[24:27], v[134:137], v[182:185], v[24:27]
	v_mfma_f32_16x16x32_bf16 v[20:23], v[162:165], v[182:185], v[20:23]
	v_mfma_f32_16x16x32_bf16 v[16:19], v[166:169], v[182:185], v[16:19]
	v_mfma_f32_16x16x32_bf16 v[12:15], v[130:133], v[186:189], v[12:15]
	v_mfma_f32_16x16x32_bf16 v[8:11], v[134:137], v[186:189], v[8:11]
	v_mfma_f32_16x16x32_bf16 v[4:7], v[162:165], v[186:189], v[4:7]
	v_mfma_f32_16x16x32_bf16 v[0:3], v[166:169], v[186:189], v[0:3]
	ds_read_b128 v[130:133], v173
	ds_read_b128 v[134:137], v173 offset:1024
	ds_read_b128 v[160:163], v173 offset:2048
	ds_read_b128 v[164:167], v173 offset:3072
	ds_read_b128 v[168:171], v128
	ds_read_b128 v[174:177], v128 offset:1024
	ds_read_b128 v[178:181], v128 offset:2048
	ds_read_b128 v[182:185], v128 offset:3072
	s_nop 0
	s_waitcnt lgkmcnt(0)
	s_nop 0
	v_mfma_f32_16x16x32_bf16 v[186:189], v[130:133], v[168:171], v[124:127]
	v_mfma_f32_16x16x32_bf16 v[120:123], v[134:137], v[168:171], v[120:123]
	v_mfma_f32_16x16x32_bf16 v[116:119], v[160:163], v[168:171], v[116:119]
	v_mfma_f32_16x16x32_bf16 v[112:115], v[164:167], v[168:171], v[112:115]
	v_mfma_f32_16x16x32_bf16 v[108:111], v[130:133], v[174:177], v[108:111]
	v_mfma_f32_16x16x32_bf16 v[104:107], v[134:137], v[174:177], v[104:107]
	v_mfma_f32_16x16x32_bf16 v[100:103], v[160:163], v[174:177], v[100:103]
	v_mfma_f32_16x16x32_bf16 v[96:99], v[164:167], v[174:177], v[96:99]
	v_mfma_f32_16x16x32_bf16 v[92:95], v[130:133], v[178:181], v[92:95]
	v_mfma_f32_16x16x32_bf16 v[88:91], v[134:137], v[178:181], v[88:91]
	v_mfma_f32_16x16x32_bf16 v[84:87], v[160:163], v[178:181], v[84:87]
	v_mfma_f32_16x16x32_bf16 v[80:83], v[164:167], v[178:181], v[80:83]
	ds_read_b128 v[124:127], v128 offset:4096
	ds_read_b128 v[168:171], v128 offset:5120
	ds_read_b128 v[174:177], v128 offset:6144
	ds_read_b128 v[178:181], v128 offset:7168
	s_waitcnt lgkmcnt(0)
	s_barrier
	v_mfma_f32_16x16x32_bf16 v[76:79], v[130:133], v[182:185], v[76:79]
	v_mfma_f32_16x16x32_bf16 v[72:75], v[134:137], v[182:185], v[72:75]
	v_mfma_f32_16x16x32_bf16 v[68:71], v[160:163], v[182:185], v[68:71]
	v_mfma_f32_16x16x32_bf16 v[64:67], v[164:167], v[182:185], v[64:67]
	v_mfma_f32_16x16x32_bf16 v[60:63], v[130:133], v[124:127], v[60:63]
	v_mfma_f32_16x16x32_bf16 v[56:59], v[134:137], v[124:127], v[56:59]
	v_mfma_f32_16x16x32_bf16 v[52:55], v[160:163], v[124:127], v[52:55]
	v_mfma_f32_16x16x32_bf16 v[48:51], v[164:167], v[124:127], v[48:51]
	v_mfma_f32_16x16x32_bf16 v[44:47], v[130:133], v[168:171], v[44:47]
	v_mfma_f32_16x16x32_bf16 v[40:43], v[134:137], v[168:171], v[40:43]
	v_mfma_f32_16x16x32_bf16 v[36:39], v[160:163], v[168:171], v[36:39]
	v_mfma_f32_16x16x32_bf16 v[32:35], v[164:167], v[168:171], v[32:35]
	v_mfma_f32_16x16x32_bf16 v[28:31], v[130:133], v[174:177], v[28:31]
	v_mfma_f32_16x16x32_bf16 v[24:27], v[134:137], v[174:177], v[24:27]
	v_mfma_f32_16x16x32_bf16 v[20:23], v[160:163], v[174:177], v[20:23]
	v_mfma_f32_16x16x32_bf16 v[16:19], v[164:167], v[174:177], v[16:19]
	v_mfma_f32_16x16x32_bf16 v[12:15], v[130:133], v[178:181], v[12:15]
	v_cndmask_b32_e64 v132, 1.0, v156, s[8:9]
	v_mul_f32_e32 v124, v132, v159
	v_pk_mul_f32 v[126:127], v[124:125], v[188:189] op_sel_hi:[0,1]
	v_mfma_f32_16x16x32_bf16 v[8:11], v[134:137], v[178:181], v[8:11]
	v_mul_f32_e64 v130, v124, v186
	v_mul_f32_e64 v131, v124, v187
	v_mfma_f32_16x16x32_bf16 v[4:7], v[160:163], v[178:181], v[4:7]
	v_mfma_f32_16x16x32_bf16 v[0:3], v[164:167], v[178:181], v[0:3]
	s_cbranch_vccz .LBB0_809
	v_mul_f32_e32 v125, 0xbfb8aa3b, v130
	v_exp_f32_e32 v125, v125
	v_mul_f32_e32 v133, 0xbfb8aa3b, v126
	v_mul_f32_e32 v128, 0xbfb8aa3b, v131
	v_exp_f32_e32 v128, v128
	v_add_f32_e32 v125, 1.0, v125
	v_rcp_f32_e32 v134, v125
	v_exp_f32_e32 v125, v133
	v_mul_f32_e32 v133, 0xbfb8aa3b, v127
	v_exp_f32_e32 v133, v133
	v_add_f32_e32 v128, 1.0, v128
	v_add_f32_e32 v125, 1.0, v125
	v_rcp_f32_e32 v136, v125
	v_add_f32_e32 v125, 1.0, v133
	v_rcp_f32_e32 v137, v125
	v_rcp_f32_e32 v135, v128
	v_pk_mul_f32 v[126:127], v[126:127], v[136:137]
	v_pk_mul_f32 v[130:131], v[130:131], v[134:135]

.Lgsk3_loop:
	s_add_i32 s8, s5, 0xfffe8000
	s_and_b32 s9, s5, 0x18000
	s_and_b32 s8, s8, 0x18000
	s_add_i32 s9, s4, s9
	v_add_u32_e32 v128, s8, v141
	v_or_b32_e32 v143, s8, v142
	s_add_i32 s11, s9, 0x400
	s_add_i32 s10, s9, 0x800
	s_add_i32 s8, s9, 0xc00
	s_add_i32 s5, s5, 0x8000
	s_cmp_eq_u32 s5, 0x100000
	s_waitcnt vmcnt(8) lgkmcnt(0)
	s_barrier
	v_mfma_f32_16x16x32_bf16 v[60:63], v[232:235], v[144:147], v[60:63]
	ds_read_b128 v[174:177], v128
	ds_read_b128 v[178:181], v128 offset:1024
	v_mfma_f32_16x16x32_bf16 v[44:47], v[236:239], v[144:147], v[44:47]
	ds_read_b128 v[182:185], v128 offset:2048
	ds_read_b128 v[186:189], v128 offset:3072
	v_mfma_f32_16x16x32_bf16 v[28:31], v[240:243], v[144:147], v[28:31]
	s_mov_b32 m0, s9
	v_mfma_f32_16x16x32_bf16 v[12:15], v[244:247], v[144:147], v[12:15]
	global_load_lds_dwordx4 v[136:137], off
	v_lshl_add_u64 v[136:137], v[136:137], 0, 64
	v_mfma_f32_16x16x32_bf16 v[56:59], v[232:235], v[158:161], v[56:59]
	ds_read_b128 v[144:147], v143
	v_mfma_f32_16x16x32_bf16 v[40:43], v[236:239], v[158:161], v[40:43]
	v_mfma_f32_16x16x32_bf16 v[24:27], v[240:243], v[158:161], v[24:27]
	s_mov_b32 m0, s11
	v_mfma_f32_16x16x32_bf16 v[8:11], v[244:247], v[158:161], v[8:11]
	global_load_lds_dwordx4 v[134:135], off
	v_lshl_add_u64 v[134:135], v[134:135], 0, 64
	v_mfma_f32_16x16x32_bf16 v[52:55], v[232:235], v[162:165], v[52:55]
	ds_read_b128 v[158:161], v143 offset:1024
	v_mfma_f32_16x16x32_bf16 v[36:39], v[236:239], v[162:165], v[36:39]
	v_mfma_f32_16x16x32_bf16 v[20:23], v[240:243], v[162:165], v[20:23]
	s_mov_b32 m0, s10
	v_mfma_f32_16x16x32_bf16 v[4:7], v[244:247], v[162:165], v[4:7]
	global_load_lds_dwordx4 v[132:133], off
	v_lshl_add_u64 v[132:133], v[132:133], 0, 64
	v_mfma_f32_16x16x32_bf16 v[48:51], v[232:235], v[166:169], v[48:51]
	ds_read_b128 v[162:165], v143 offset:2048
	v_mfma_f32_16x16x32_bf16 v[32:35], v[236:239], v[166:169], v[32:35]
	v_mfma_f32_16x16x32_bf16 v[16:19], v[240:243], v[166:169], v[16:19]
	s_mov_b32 m0, s8
	v_mfma_f32_16x16x32_bf16 v[0:3], v[244:247], v[166:169], v[0:3]
	global_load_lds_dwordx4 v[130:131], off
	v_lshl_add_u64 v[130:131], v[130:131], 0, 64
	s_waitcnt lgkmcnt(2)
	v_mfma_f32_16x16x32_bf16 v[124:127], v[174:177], v[144:147], v[124:127]
	ds_read_b128 v[166:169], v143 offset:3072
	v_mfma_f32_16x16x32_bf16 v[108:111], v[178:181], v[144:147], v[108:111]
	ds_read_b128 v[232:235], v128 offset:4096
	ds_read_b128 v[236:239], v128 offset:5120
	v_mfma_f32_16x16x32_bf16 v[92:95], v[182:185], v[144:147], v[92:95]
	ds_read_b128 v[240:243], v128 offset:6144
	ds_read_b128 v[244:247], v128 offset:7168
	v_mfma_f32_16x16x32_bf16 v[76:79], v[186:189], v[144:147], v[76:79]
	s_waitcnt lgkmcnt(6)
	v_mfma_f32_16x16x32_bf16 v[120:123], v[174:177], v[158:161], v[120:123]
	v_mfma_f32_16x16x32_bf16 v[104:107], v[178:181], v[158:161], v[104:107]
	v_mfma_f32_16x16x32_bf16 v[88:91], v[182:185], v[158:161], v[88:91]
	v_mfma_f32_16x16x32_bf16 v[72:75], v[186:189], v[158:161], v[72:75]
	s_waitcnt lgkmcnt(5)
	v_mfma_f32_16x16x32_bf16 v[116:119], v[174:177], v[162:165], v[116:119]
	v_mfma_f32_16x16x32_bf16 v[100:103], v[178:181], v[162:165], v[100:103]
	v_mfma_f32_16x16x32_bf16 v[84:87], v[182:185], v[162:165], v[84:87]
	v_mfma_f32_16x16x32_bf16 v[68:71], v[186:189], v[162:165], v[68:71]
	s_waitcnt lgkmcnt(4)
	v_mfma_f32_16x16x32_bf16 v[112:115], v[174:177], v[166:169], v[112:115]
	v_mfma_f32_16x16x32_bf16 v[96:99], v[178:181], v[166:169], v[96:99]
	v_mfma_f32_16x16x32_bf16 v[80:83], v[182:185], v[166:169], v[80:83]
	v_mfma_f32_16x16x32_bf16 v[64:67], v[186:189], v[166:169], v[64:67]
	s_cbranch_scc0 .Lgsk3_loop
	s_waitcnt lgkmcnt(0)
	v_mfma_f32_16x16x32_bf16 v[60:63], v[232:235], v[144:147], v[60:63]
	v_mfma_f32_16x16x32_bf16 v[44:47], v[236:239], v[144:147], v[44:47]
	v_mfma_f32_16x16x32_bf16 v[28:31], v[240:243], v[144:147], v[28:31]
	v_mfma_f32_16x16x32_bf16 v[12:15], v[244:247], v[144:147], v[12:15]
	v_mfma_f32_16x16x32_bf16 v[56:59], v[232:235], v[158:161], v[56:59]
	v_mfma_f32_16x16x32_bf16 v[40:43], v[236:239], v[158:161], v[40:43]
	v_mfma_f32_16x16x32_bf16 v[24:27], v[240:243], v[158:161], v[24:27]
	v_mfma_f32_16x16x32_bf16 v[8:11], v[244:247], v[158:161], v[8:11]
	v_mfma_f32_16x16x32_bf16 v[52:55], v[232:235], v[162:165], v[52:55]
	v_mfma_f32_16x16x32_bf16 v[36:39], v[236:239], v[162:165], v[36:39]
	v_mfma_f32_16x16x32_bf16 v[20:23], v[240:243], v[162:165], v[20:23]
	v_mfma_f32_16x16x32_bf16 v[4:7], v[244:247], v[162:165], v[4:7]
	v_mfma_f32_16x16x32_bf16 v[48:51], v[232:235], v[166:169], v[48:51]
	v_mfma_f32_16x16x32_bf16 v[32:35], v[236:239], v[166:169], v[32:35]
	v_mfma_f32_16x16x32_bf16 v[16:19], v[240:243], v[166:169], v[16:19]
	v_mfma_f32_16x16x32_bf16 v[0:3], v[244:247], v[166:169], v[0:3]
	s_waitcnt vmcnt(8)
	s_barrier
	v_add_u32_e32 v128, 0x8000, v141
	v_or_b32_e32 v143, 0x8000, v142
	ds_read_b128 v[130:133], v143
	ds_read_b128 v[134:137], v143 offset:1024
	ds_read_b128 v[144:147], v143 offset:2048
	ds_read_b128 v[158:161], v143 offset:3072
	ds_read_b128 v[162:165], v128
	ds_read_b128 v[166:169], v128 offset:1024
	ds_read_b128 v[174:177], v128 offset:2048
	ds_read_b128 v[178:181], v128 offset:3072
	v_or_b32_e32 v143, 0x10000, v142
	s_waitcnt lgkmcnt(0)
	s_ashr_i32 s13, s12, 31
	v_mfma_f32_16x16x32_bf16 v[124:127], v[162:165], v[130:133], v[124:127]
	s_lshl_b64 s[4:5], s[12:13], 2
	s_add_u32 s4, s62, s4
	s_addc_u32 s5, s63, s5
	v_mfma_f32_16x16x32_bf16 v[120:123], v[162:165], v[134:137], v[120:123]
	v_mfma_f32_16x16x32_bf16 v[116:119], v[162:165], v[144:147], v[116:119]
	v_mfma_f32_16x16x32_bf16 v[112:115], v[162:165], v[158:161], v[112:115]
	v_mfma_f32_16x16x32_bf16 v[108:111], v[166:169], v[130:133], v[108:111]
	v_mfma_f32_16x16x32_bf16 v[104:107], v[166:169], v[134:137], v[104:107]
	v_mfma_f32_16x16x32_bf16 v[100:103], v[166:169], v[144:147], v[100:103]
	v_mfma_f32_16x16x32_bf16 v[96:99], v[166:169], v[158:161], v[96:99]
	v_mfma_f32_16x16x32_bf16 v[92:95], v[174:177], v[130:133], v[92:95]
	v_mfma_f32_16x16x32_bf16 v[88:91], v[174:177], v[134:137], v[88:91]
	v_mfma_f32_16x16x32_bf16 v[84:87], v[174:177], v[144:147], v[84:87]
	v_mfma_f32_16x16x32_bf16 v[80:83], v[174:177], v[158:161], v[80:83]
	v_mfma_f32_16x16x32_bf16 v[76:79], v[178:181], v[130:133], v[76:79]
	v_mfma_f32_16x16x32_bf16 v[72:75], v[178:181], v[134:137], v[72:75]
	v_mfma_f32_16x16x32_bf16 v[68:71], v[178:181], v[144:147], v[68:71]
	v_mfma_f32_16x16x32_bf16 v[64:67], v[178:181], v[158:161], v[64:67]
	ds_read_b128 v[162:165], v128 offset:4096
	ds_read_b128 v[166:169], v128 offset:5120
	ds_read_b128 v[174:177], v128 offset:6144
	ds_read_b128 v[178:181], v128 offset:7168
	s_waitcnt lgkmcnt(0)
	s_waitcnt vmcnt(4)
	s_barrier
	v_mfma_f32_16x16x32_bf16 v[60:63], v[162:165], v[130:133], v[60:63]
	v_add_u32_e32 v128, 0x10000, v141
	v_mfma_f32_16x16x32_bf16 v[56:59], v[162:165], v[134:137], v[56:59]
	v_mfma_f32_16x16x32_bf16 v[52:55], v[162:165], v[144:147], v[52:55]
	v_mfma_f32_16x16x32_bf16 v[48:51], v[162:165], v[158:161], v[48:51]
	v_mfma_f32_16x16x32_bf16 v[44:47], v[166:169], v[130:133], v[44:47]
	v_mfma_f32_16x16x32_bf16 v[40:43], v[166:169], v[134:137], v[40:43]
	v_mfma_f32_16x16x32_bf16 v[36:39], v[166:169], v[144:147], v[36:39]
	v_mfma_f32_16x16x32_bf16 v[32:35], v[166:169], v[158:161], v[32:35]
	v_mfma_f32_16x16x32_bf16 v[28:31], v[174:177], v[130:133], v[28:31]
	v_mfma_f32_16x16x32_bf16 v[24:27], v[174:177], v[134:137], v[24:27]
	v_mfma_f32_16x16x32_bf16 v[20:23], v[174:177], v[144:147], v[20:23]
	v_mfma_f32_16x16x32_bf16 v[16:19], v[174:177], v[158:161], v[16:19]
	v_mfma_f32_16x16x32_bf16 v[12:15], v[178:181], v[130:133], v[12:15]
	v_mfma_f32_16x16x32_bf16 v[8:11], v[178:181], v[134:137], v[8:11]
	v_mfma_f32_16x16x32_bf16 v[4:7], v[178:181], v[144:147], v[4:7]
	v_mfma_f32_16x16x32_bf16 v[0:3], v[178:181], v[158:161], v[0:3]
	ds_read_b128 v[130:133], v143
	ds_read_b128 v[134:137], v143 offset:1024
	ds_read_b128 v[144:147], v143 offset:2048
	ds_read_b128 v[158:161], v143 offset:3072
	ds_read_b128 v[162:165], v128
	ds_read_b128 v[166:169], v128 offset:1024
	ds_read_b128 v[174:177], v128 offset:2048
	ds_read_b128 v[178:181], v128 offset:3072
	s_nop 0
	s_waitcnt lgkmcnt(0)
	s_nop 0
	v_mfma_f32_16x16x32_bf16 v[124:127], v[162:165], v[130:133], v[124:127]
	v_mfma_f32_16x16x32_bf16 v[120:123], v[162:165], v[134:137], v[120:123]
	v_mfma_f32_16x16x32_bf16 v[116:119], v[162:165], v[144:147], v[116:119]
	v_mfma_f32_16x16x32_bf16 v[112:115], v[162:165], v[158:161], v[112:115]
	v_mfma_f32_16x16x32_bf16 v[108:111], v[166:169], v[130:133], v[108:111]
	v_mfma_f32_16x16x32_bf16 v[104:107], v[166:169], v[134:137], v[104:107]
	v_mfma_f32_16x16x32_bf16 v[100:103], v[166:169], v[144:147], v[100:103]
	v_mfma_f32_16x16x32_bf16 v[96:99], v[166:169], v[158:161], v[96:99]
	v_mfma_f32_16x16x32_bf16 v[92:95], v[174:177], v[130:133], v[92:95]
	v_mfma_f32_16x16x32_bf16 v[88:91], v[174:177], v[134:137], v[88:91]
	v_mfma_f32_16x16x32_bf16 v[84:87], v[174:177], v[144:147], v[84:87]
	v_mfma_f32_16x16x32_bf16 v[80:83], v[174:177], v[158:161], v[80:83]
	v_mfma_f32_16x16x32_bf16 v[76:79], v[178:181], v[130:133], v[76:79]
	v_mfma_f32_16x16x32_bf16 v[72:75], v[178:181], v[134:137], v[72:75]
	v_mfma_f32_16x16x32_bf16 v[68:71], v[178:181], v[144:147], v[68:71]
	v_mfma_f32_16x16x32_bf16 v[64:67], v[178:181], v[158:161], v[64:67]
	ds_read_b128 v[162:165], v128 offset:4096
	ds_read_b128 v[166:169], v128 offset:5120
	ds_read_b128 v[174:177], v128 offset:6144
	ds_read_b128 v[178:181], v128 offset:7168
	s_waitcnt lgkmcnt(0)
	s_waitcnt vmcnt(0)
	s_barrier
	v_mfma_f32_16x16x32_bf16 v[60:63], v[162:165], v[130:133], v[60:63]
	v_add_u32_e32 v128, 0x18000, v141
	v_or_b32_e32 v141, 0x18000, v142
	v_mfma_f32_16x16x32_bf16 v[56:59], v[162:165], v[134:137], v[56:59]
	v_mfma_f32_16x16x32_bf16 v[52:55], v[162:165], v[144:147], v[52:55]
	v_mfma_f32_16x16x32_bf16 v[48:51], v[162:165], v[158:161], v[48:51]
	v_mfma_f32_16x16x32_bf16 v[44:47], v[166:169], v[130:133], v[44:47]
	v_mfma_f32_16x16x32_bf16 v[40:43], v[166:169], v[134:137], v[40:43]
	v_mfma_f32_16x16x32_bf16 v[36:39], v[166:169], v[144:147], v[36:39]
	v_mfma_f32_16x16x32_bf16 v[32:35], v[166:169], v[158:161], v[32:35]
	v_mfma_f32_16x16x32_bf16 v[28:31], v[174:177], v[130:133], v[28:31]
	v_mfma_f32_16x16x32_bf16 v[24:27], v[174:177], v[134:137], v[24:27]
	v_mfma_f32_16x16x32_bf16 v[20:23], v[174:177], v[144:147], v[20:23]
	v_mfma_f32_16x16x32_bf16 v[16:19], v[174:177], v[158:161], v[16:19]
	v_mfma_f32_16x16x32_bf16 v[12:15], v[178:181], v[130:133], v[12:15]
	v_mfma_f32_16x16x32_bf16 v[8:11], v[178:181], v[134:137], v[8:11]
	v_mfma_f32_16x16x32_bf16 v[4:7], v[178:181], v[144:147], v[4:7]
	v_mfma_f32_16x16x32_bf16 v[0:3], v[178:181], v[158:161], v[0:3]
	ds_read_b128 v[130:133], v141
	ds_read_b128 v[134:137], v141 offset:1024
	ds_read_b128 v[142:145], v141 offset:2048
	ds_read_b128 v[158:161], v141 offset:3072
	ds_read_b128 v[162:165], v128
	ds_read_b128 v[166:169], v128 offset:1024
	ds_read_b128 v[174:177], v128 offset:2048
	ds_read_b128 v[178:181], v128 offset:3072
	s_nop 0
	s_waitcnt lgkmcnt(0)
	s_nop 0
	v_mfma_f32_16x16x32_bf16 v[124:127], v[162:165], v[130:133], v[124:127]
	v_mfma_f32_16x16x32_bf16 v[120:123], v[162:165], v[134:137], v[120:123]
	v_mfma_f32_16x16x32_bf16 v[116:119], v[162:165], v[142:145], v[116:119]
	v_mfma_f32_16x16x32_bf16 v[162:165], v[162:165], v[158:161], v[112:115]
	v_mfma_f32_16x16x32_bf16 v[108:111], v[166:169], v[130:133], v[108:111]
	v_mfma_f32_16x16x32_bf16 v[104:107], v[166:169], v[134:137], v[104:107]
	v_mfma_f32_16x16x32_bf16 v[100:103], v[166:169], v[142:145], v[100:103]
	v_mfma_f32_16x16x32_bf16 v[96:99], v[166:169], v[158:161], v[96:99]
	v_mfma_f32_16x16x32_bf16 v[92:95], v[174:177], v[130:133], v[92:95]
	v_mfma_f32_16x16x32_bf16 v[88:91], v[174:177], v[134:137], v[88:91]
	v_mfma_f32_16x16x32_bf16 v[84:87], v[174:177], v[142:145], v[84:87]
	v_mfma_f32_16x16x32_bf16 v[80:83], v[174:177], v[158:161], v[80:83]
	v_mfma_f32_16x16x32_bf16 v[76:79], v[178:181], v[130:133], v[76:79]
	v_mfma_f32_16x16x32_bf16 v[72:75], v[178:181], v[134:137], v[72:75]
	v_mfma_f32_16x16x32_bf16 v[68:71], v[178:181], v[142:145], v[68:71]
	v_mfma_f32_16x16x32_bf16 v[64:67], v[178:181], v[158:161], v[64:67]
	ds_read_b128 v[112:115], v128 offset:4096
	ds_read_b128 v[166:169], v128 offset:5120
	ds_read_b128 v[174:177], v128 offset:6144
	ds_read_b128 v[178:181], v128 offset:7168
	s_waitcnt lgkmcnt(0)
	s_barrier
	v_mfma_f32_16x16x32_bf16 v[60:63], v[112:115], v[130:133], v[60:63]
	v_mfma_f32_16x16x32_bf16 v[56:59], v[112:115], v[134:137], v[56:59]
	v_mfma_f32_16x16x32_bf16 v[52:55], v[112:115], v[142:145], v[52:55]
	v_mfma_f32_16x16x32_bf16 v[48:51], v[112:115], v[158:161], v[48:51]
	v_lshlrev_b32_e32 v114, 3, v139
	v_lshlrev_b32_e32 v113, 8, v140
	v_and_b32_e32 v114, 8, v114
	v_add3_u32 v113, s38, v113, v114
	v_lshlrev_b32_e32 v114, 4, v139
	v_mfma_f32_16x16x32_bf16 v[44:47], v[166:169], v[130:133], v[44:47]
	v_lshrrev_b32_e32 v112, 5, v138
	v_xor_b32_e32 v115, v112, v140
	v_lshl_add_u32 v115, v115, 4, v113
	v_mfma_f32_16x16x32_bf16 v[28:31], v[174:177], v[130:133], v[28:31]
	v_mfma_f32_16x16x32_bf16 v[12:15], v[178:181], v[130:133], v[12:15]
	global_load_dwordx4 v[130:133], v114, s[4:5]
	s_waitcnt vmcnt(0)
	v_pk_mul_f32 v[126:127], v[126:127], v[132:133]
	v_pk_mul_f32 v[124:125], v[124:125], v[130:131]
	v_pk_mul_f32 v[122:123], v[122:123], v[132:133]
	v_pk_mul_f32 v[120:121], v[120:121], v[130:131]
	v_cvt_pk_bf16_f32 v124, v124, v125
	v_cvt_pk_bf16_f32 v125, v126, v127
	v_cvt_pk_bf16_f32 v120, v120, v121
	v_cvt_pk_bf16_f32 v121, v122, v123
	v_pk_mul_f32 v[118:119], v[118:119], v[132:133]
	v_pk_mul_f32 v[116:117], v[116:117], v[130:131]
	ds_write2st64_b64 v115, v[124:125], v[120:121] offset1:8
	v_cvt_pk_bf16_f32 v116, v116, v117
	v_cvt_pk_bf16_f32 v117, v118, v119
	v_pk_mul_f32 v[118:119], v[164:165], v[132:133]
	v_pk_mul_f32 v[120:121], v[162:163], v[130:131]
	v_mfma_f32_16x16x32_bf16 v[36:39], v[166:169], v[142:145], v[36:39]
	v_cvt_pk_bf16_f32 v120, v120, v121
	v_cvt_pk_bf16_f32 v121, v118, v119
	ds_write2st64_b64 v115, v[116:117], v[120:121] offset0:16 offset1:24
	global_load_dwordx4 v[116:119], v114, s[4:5] offset:64
	v_bitop3_b32 v115, v112, v140, 2 bitop3:0x36
	v_lshl_add_u32 v115, v115, 4, v113
	v_mfma_f32_16x16x32_bf16 v[32:35], v[166:169], v[158:161], v[32:35]
	s_waitcnt vmcnt(0)
	v_pk_mul_f32 v[102:103], v[102:103], v[118:119]
	v_pk_mul_f32 v[100:101], v[100:101], v[116:117]
	v_pk_mul_f32 v[98:99], v[98:99], v[118:119]
	v_pk_mul_f32 v[96:97], v[96:97], v[116:117]
	v_cvt_pk_bf16_f32 v100, v100, v101
	v_cvt_pk_bf16_f32 v101, v102, v103
	v_cvt_pk_bf16_f32 v96, v96, v97
	v_cvt_pk_bf16_f32 v97, v98, v99
	ds_write2st64_b64 v115, v[100:101], v[96:97] offset0:16 offset1:24
	global_load_dwordx4 v[96:99], v114, s[4:5] offset:128
	v_bitop3_b32 v100, v112, v140, 4 bitop3:0x36
	v_lshl_add_u32 v100, v100, 4, v113
	v_mfma_f32_16x16x32_bf16 v[20:23], v[174:177], v[142:145], v[20:23]
	v_mul_f32_e64 v110, v110, v118
	v_mul_f32_e64 v111, v111, v119
	v_pk_mul_f32 v[108:109], v[108:109], v[116:117]
	v_pk_mul_f32 v[106:107], v[106:107], v[118:119]
	v_mfma_f32_16x16x32_bf16 v[16:19], v[174:177], v[158:161], v[16:19]
	v_mul_f32_e64 v104, v104, v116
	v_mul_f32_e64 v105, v105, v117
	v_cvt_pk_bf16_f32 v108, v108, v109
	v_cvt_pk_bf16_f32 v109, v110, v111
	v_mfma_f32_16x16x32_bf16 v[0:3], v[178:181], v[158:161], v[0:3]
	v_cvt_pk_bf16_f32 v104, v104, v105
	v_cvt_pk_bf16_f32 v105, v106, v107
	ds_write2st64_b64 v115, v[108:109], v[104:105] offset1:8
	v_mfma_f32_16x16x32_bf16 v[8:11], v[178:181], v[134:137], v[8:11]
	s_waitcnt vmcnt(0)
	v_pk_mul_f32 v[86:87], v[86:87], v[98:99]
	v_pk_mul_f32 v[84:85], v[84:85], v[96:97]
	v_pk_mul_f32 v[82:83], v[82:83], v[98:99]
	v_pk_mul_f32 v[80:81], v[80:81], v[96:97]
	v_cvt_pk_bf16_f32 v84, v84, v85
	v_cvt_pk_bf16_f32 v85, v86, v87
	v_cvt_pk_bf16_f32 v80, v80, v81
	v_cvt_pk_bf16_f32 v81, v82, v83
	ds_write2st64_b64 v100, v[84:85], v[80:81] offset0:16 offset1:24
	global_load_dwordx4 v[80:83], v114, s[4:5] offset:192
	v_bitop3_b32 v84, v112, v140, 6 bitop3:0x36
	v_lshl_add_u32 v84, v84, 4, v113
	v_mfma_f32_16x16x32_bf16 v[40:43], v[166:169], v[134:137], v[40:43]
	v_mul_f32_e64 v94, v94, v98
	v_mul_f32_e64 v95, v95, v99
	v_pk_mul_f32 v[92:93], v[92:93], v[96:97]
	v_pk_mul_f32 v[90:91], v[90:91], v[98:99]
	v_mfma_f32_16x16x32_bf16 v[24:27], v[174:177], v[134:137], v[24:27]
	v_mul_f32_e64 v88, v88, v96
	v_mul_f32_e64 v89, v89, v97
	v_cvt_pk_bf16_f32 v92, v92, v93
	v_cvt_pk_bf16_f32 v93, v94, v95
	v_mfma_f32_16x16x32_bf16 v[4:7], v[178:181], v[142:145], v[4:7]
	v_cvt_pk_bf16_f32 v88, v88, v89
	v_cvt_pk_bf16_f32 v89, v90, v91
	ds_write2st64_b64 v100, v[92:93], v[88:89] offset1:8
	s_waitcnt vmcnt(0)
	v_pk_mul_f32 v[70:71], v[70:71], v[82:83]
	v_pk_mul_f32 v[68:69], v[68:69], v[80:81]
	v_pk_mul_f32 v[66:67], v[66:67], v[82:83]
	v_pk_mul_f32 v[64:65], v[64:65], v[80:81]
	v_cvt_pk_bf16_f32 v68, v68, v69
	v_cvt_pk_bf16_f32 v69, v70, v71
	v_cvt_pk_bf16_f32 v64, v64, v65
	v_cvt_pk_bf16_f32 v65, v66, v67
	ds_write2st64_b64 v84, v[68:69], v[64:65] offset0:16 offset1:24
	global_load_dwordx4 v[64:67], v114, s[4:5] offset:256
	v_bitop3_b32 v68, v112, v140, 8 bitop3:0x36
	v_lshl_add_u32 v68, v68, 4, v113
	v_pk_mul_f32 v[78:79], v[78:79], v[82:83]
	v_pk_mul_f32 v[76:77], v[76:77], v[80:81]
	v_pk_mul_f32 v[74:75], v[74:75], v[82:83]
	v_pk_mul_f32 v[72:73], v[72:73], v[80:81]
	v_cvt_pk_bf16_f32 v76, v76, v77
	v_cvt_pk_bf16_f32 v77, v78, v79
	v_cvt_pk_bf16_f32 v72, v72, v73
	v_cvt_pk_bf16_f32 v73, v74, v75
	ds_write2st64_b64 v84, v[76:77], v[72:73] offset1:8
	s_waitcnt vmcnt(0)
	v_pk_mul_f32 v[54:55], v[54:55], v[66:67]
	v_pk_mul_f32 v[52:53], v[52:53], v[64:65]
	v_pk_mul_f32 v[50:51], v[50:51], v[66:67]
	v_pk_mul_f32 v[48:49], v[48:49], v[64:65]
	v_cvt_pk_bf16_f32 v52, v52, v53
	v_cvt_pk_bf16_f32 v53, v54, v55
	v_cvt_pk_bf16_f32 v48, v48, v49
	v_cvt_pk_bf16_f32 v49, v50, v51
	ds_write2st64_b64 v68, v[52:53], v[48:49] offset0:16 offset1:24
	global_load_dwordx4 v[48:51], v114, s[4:5] offset:320
	v_bitop3_b32 v52, v112, v140, 10 bitop3:0x36
	v_lshl_add_u32 v52, v52, 4, v113
	v_pk_mul_f32 v[62:63], v[62:63], v[66:67]
	v_pk_mul_f32 v[60:61], v[60:61], v[64:65]
	v_pk_mul_f32 v[58:59], v[58:59], v[66:67]
	v_pk_mul_f32 v[56:57], v[56:57], v[64:65]
	v_cvt_pk_bf16_f32 v60, v60, v61
	v_cvt_pk_bf16_f32 v61, v62, v63
	v_cvt_pk_bf16_f32 v56, v56, v57
	v_cvt_pk_bf16_f32 v57, v58, v59
	ds_write2st64_b64 v68, v[60:61], v[56:57] offset1:8
	s_waitcnt vmcnt(0)
	v_pk_mul_f32 v[38:39], v[38:39], v[50:51]
	v_pk_mul_f32 v[36:37], v[36:37], v[48:49]
	v_pk_mul_f32 v[34:35], v[34:35], v[50:51]
	v_pk_mul_f32 v[32:33], v[32:33], v[48:49]
	v_cvt_pk_bf16_f32 v36, v36, v37
	v_cvt_pk_bf16_f32 v37, v38, v39
	v_cvt_pk_bf16_f32 v32, v32, v33
	v_cvt_pk_bf16_f32 v33, v34, v35
	ds_write2st64_b64 v52, v[36:37], v[32:33] offset0:16 offset1:24
	global_load_dwordx4 v[32:35], v114, s[4:5] offset:384
	v_bitop3_b32 v36, v112, v140, 12 bitop3:0x36
	v_lshl_add_u32 v36, v36, 4, v113
	v_pk_mul_f32 v[46:47], v[46:47], v[50:51]
	v_pk_mul_f32 v[44:45], v[44:45], v[48:49]
	v_pk_mul_f32 v[42:43], v[42:43], v[50:51]
	v_pk_mul_f32 v[40:41], v[40:41], v[48:49]
	v_cvt_pk_bf16_f32 v44, v44, v45
	v_cvt_pk_bf16_f32 v45, v46, v47
	v_cvt_pk_bf16_f32 v40, v40, v41
	v_cvt_pk_bf16_f32 v41, v42, v43
	ds_write2st64_b64 v52, v[44:45], v[40:41] offset1:8
	s_waitcnt vmcnt(0)
	v_pk_mul_f32 v[22:23], v[22:23], v[34:35]
	v_pk_mul_f32 v[20:21], v[20:21], v[32:33]
	v_pk_mul_f32 v[18:19], v[18:19], v[34:35]
	v_pk_mul_f32 v[16:17], v[16:17], v[32:33]
	v_cvt_pk_bf16_f32 v20, v20, v21
	v_cvt_pk_bf16_f32 v21, v22, v23
	v_cvt_pk_bf16_f32 v16, v16, v17
	v_cvt_pk_bf16_f32 v17, v18, v19
	ds_write2st64_b64 v36, v[20:21], v[16:17] offset0:16 offset1:24
	global_load_dwordx4 v[16:19], v114, s[4:5] offset:448
	s_lshr_b32 s4, s40, 6
	s_and_b32 s5, s39, -16
	s_or_b32 s4, s4, s5
	v_bitop3_b32 v20, v112, v140, 14 bitop3:0x36
	s_ashr_i32 s5, s4, 31
	v_pk_mul_f32 v[30:31], v[30:31], v[34:35]
	v_pk_mul_f32 v[28:29], v[28:29], v[32:33]
	v_pk_mul_f32 v[26:27], v[26:27], v[34:35]
	v_pk_mul_f32 v[24:25], v[24:25], v[32:33]
	v_lshl_add_u32 v20, v20, 4, v113
	s_lshl_b64 s[4:5], s[4:5], 19
	v_cvt_pk_bf16_f32 v28, v28, v29
	v_cvt_pk_bf16_f32 v29, v30, v31
	v_cvt_pk_bf16_f32 v24, v24, v25
	v_cvt_pk_bf16_f32 v25, v26, v27
	s_add_u32 s4, s26, s4
	ds_write2st64_b64 v36, v[28:29], v[24:25] offset1:8
	s_addc_u32 s5, s27, s5
	s_and_b32 s8, s12, 0xf80
	s_lshl_b32 s8, s8, 1
	s_add_u32 s4, s4, s8
	s_addc_u32 s5, s5, 0
	s_waitcnt vmcnt(0)
	v_pk_mul_f32 v[2:3], v[2:3], v[18:19]
	v_pk_mul_f32 v[0:1], v[0:1], v[16:17]
	v_pk_mul_f32 v[14:15], v[14:15], v[18:19]
	v_pk_mul_f32 v[12:13], v[12:13], v[16:17]
	v_pk_mul_f32 v[10:11], v[10:11], v[18:19]
	v_pk_mul_f32 v[8:9], v[8:9], v[16:17]
	v_cvt_pk_bf16_f32 v0, v0, v1
	v_cvt_pk_bf16_f32 v1, v2, v3
	v_xor_b32_e32 v3, v139, v138
	v_cvt_pk_bf16_f32 v12, v12, v13
	v_cvt_pk_bf16_f32 v13, v14, v15
	v_cvt_pk_bf16_f32 v8, v8, v9
	v_cvt_pk_bf16_f32 v9, v10, v11
	v_lshlrev_b32_e32 v3, 4, v3
	ds_write2st64_b64 v20, v[12:13], v[8:9] offset1:8
	v_pk_mul_f32 v[6:7], v[6:7], v[18:19]
	v_pk_mul_f32 v[4:5], v[4:5], v[16:17]
	v_lshlrev_b32_e32 v2, 8, v139
	v_and_b32_e32 v8, 0xf0, v3
	v_cvt_pk_bf16_f32 v4, v4, v5
	v_cvt_pk_bf16_f32 v5, v6, v7
	v_add3_u32 v2, s38, v2, v8
	ds_write2st64_b64 v20, v[4:5], v[0:1] offset0:16 offset1:24
	ds_read_b128 v[2:5], v2
	v_lshlrev_b32_e32 v0, 4, v138
	v_and_b32_e32 v128, 0xf0, v0
	v_lshl_add_u64 v[0:1], s[4:5], 0, v[128:129]
	v_lshlrev_b32_e32 v128, 13, v139
	v_lshl_add_u64 v[6:7], v[0:1], 0, v[128:129]
	s_waitcnt lgkmcnt(0)
	global_store_dwordx4 v[6:7], v[2:5], off
	v_or_b32_e32 v6, 4, v139
	v_lshlrev_b32_e32 v128, 13, v6
	v_bitop3_b32 v3, v139, v138, 4 bitop3:0x36
	v_lshlrev_b32_e32 v3, 4, v3
	v_lshlrev_b32_e32 v2, 8, v6
	v_and_b32_e32 v3, 0xf0, v3
	v_add3_u32 v2, s38, v2, v3
	ds_read_b128 v[2:5], v2
	v_lshl_add_u64 v[6:7], v[0:1], 0, v[128:129]
	s_waitcnt lgkmcnt(0)
	global_store_dwordx4 v[6:7], v[2:5], off
	s_nop 1
	v_bitop3_b32 v3, v139, v138, 8 bitop3:0x36
	v_or_b32_e32 v6, 8, v139
	v_lshlrev_b32_e32 v3, 4, v3
	v_lshlrev_b32_e32 v2, 8, v6
	v_and_b32_e32 v3, 0xf0, v3
	v_add3_u32 v2, s38, v2, v3
	ds_read_b128 v[2:5], v2
	v_lshlrev_b32_e32 v128, 13, v6
	v_lshl_add_u64 v[6:7], v[0:1], 0, v[128:129]
	s_waitcnt lgkmcnt(0)
	global_store_dwordx4 v[6:7], v[2:5], off
	s_nop 1
	v_bitop3_b32 v3, v139, v138, 12 bitop3:0x36
	v_or_b32_e32 v6, 12, v139
	v_lshlrev_b32_e32 v3, 4, v3
	v_lshlrev_b32_e32 v2, 8, v6
	v_and_b32_e32 v3, 0xf0, v3
	v_add3_u32 v2, s38, v2, v3
	ds_read_b128 v[2:5], v2
	v_lshlrev_b32_e32 v128, 13, v6
	v_lshl_add_u64 v[6:7], v[0:1], 0, v[128:129]
	s_waitcnt lgkmcnt(0)
	global_store_dwordx4 v[6:7], v[2:5], off
	v_or_b32_e32 v6, 16, v139
	s_nop 0
	v_lshlrev_b32_e32 v2, 8, v6
	v_add3_u32 v2, s38, v2, v8
	ds_read_b128 v[2:5], v2
	v_lshlrev_b32_e32 v128, 13, v6
	v_lshl_add_u64 v[6:7], v[0:1], 0, v[128:129]
	s_waitcnt lgkmcnt(0)
	global_store_dwordx4 v[6:7], v[2:5], off
	s_nop 1
	v_bitop3_b32 v3, v139, v138, 20 bitop3:0x36
	v_or_b32_e32 v6, 20, v139
	v_lshlrev_b32_e32 v3, 4, v3
	v_lshlrev_b32_e32 v2, 8, v6
	v_and_b32_e32 v3, 0xf0, v3
	v_add3_u32 v2, s38, v2, v3
	ds_read_b128 v[2:5], v2
	v_lshlrev_b32_e32 v128, 13, v6
	v_lshl_add_u64 v[6:7], v[0:1], 0, v[128:129]
	s_waitcnt lgkmcnt(0)
	global_store_dwordx4 v[6:7], v[2:5], off
	s_nop 1
	v_bitop3_b32 v3, v139, v138, 24 bitop3:0x36
	v_or_b32_e32 v6, 24, v139
	v_lshlrev_b32_e32 v3, 4, v3
	v_lshlrev_b32_e32 v2, 8, v6
	v_and_b32_e32 v3, 0xf0, v3
	v_add3_u32 v2, s38, v2, v3
	ds_read_b128 v[2:5], v2
	v_lshlrev_b32_e32 v128, 13, v6
	v_lshl_add_u64 v[6:7], v[0:1], 0, v[128:129]
	s_waitcnt lgkmcnt(0)
	global_store_dwordx4 v[6:7], v[2:5], off
	s_nop 1
	v_bitop3_b32 v3, v139, v138, 28 bitop3:0x36
	v_or_b32_e32 v6, 28, v139
	v_lshlrev_b32_e32 v3, 4, v3
	v_lshlrev_b32_e32 v2, 8, v6
	v_and_b32_e32 v3, 0xf0, v3
	v_add3_u32 v2, s38, v2, v3
	ds_read_b128 v[2:5], v2
	v_lshlrev_b32_e32 v128, 13, v6
	v_lshl_add_u64 v[6:7], v[0:1], 0, v[128:129]
	s_waitcnt lgkmcnt(0)
	global_store_dwordx4 v[6:7], v[2:5], off
	v_or_b32_e32 v6, 32, v139
	s_nop 0
	v_lshlrev_b32_e32 v2, 8, v6
	v_add3_u32 v2, s38, v2, v8
	ds_read_b128 v[2:5], v2
	v_lshlrev_b32_e32 v128, 13, v6
	v_lshl_add_u64 v[6:7], v[0:1], 0, v[128:129]
	s_waitcnt lgkmcnt(0)
	global_store_dwordx4 v[6:7], v[2:5], off
	s_nop 1
	v_bitop3_b32 v3, v139, v138, 36 bitop3:0x36
	v_or_b32_e32 v6, 36, v139
	v_lshlrev_b32_e32 v3, 4, v3
	v_lshlrev_b32_e32 v2, 8, v6
	v_and_b32_e32 v3, 0xf0, v3
	v_add3_u32 v2, s38, v2, v3
	ds_read_b128 v[2:5], v2
	v_lshlrev_b32_e32 v128, 13, v6
	v_lshl_add_u64 v[6:7], v[0:1], 0, v[128:129]
	s_waitcnt lgkmcnt(0)
	global_store_dwordx4 v[6:7], v[2:5], off
	s_nop 1
	v_bitop3_b32 v3, v139, v138, 40 bitop3:0x36
	v_or_b32_e32 v6, 40, v139
	v_lshlrev_b32_e32 v3, 4, v3
	v_lshlrev_b32_e32 v2, 8, v6
	v_and_b32_e32 v3, 0xf0, v3
	v_add3_u32 v2, s38, v2, v3
	ds_read_b128 v[2:5], v2
	v_lshlrev_b32_e32 v128, 13, v6
	v_lshl_add_u64 v[6:7], v[0:1], 0, v[128:129]
	s_waitcnt lgkmcnt(0)
	global_store_dwordx4 v[6:7], v[2:5], off
	s_nop 1
	v_bitop3_b32 v3, v139, v138, 44 bitop3:0x36
	v_or_b32_e32 v6, 44, v139
	v_lshlrev_b32_e32 v3, 4, v3
	v_lshlrev_b32_e32 v2, 8, v6
	v_and_b32_e32 v3, 0xf0, v3
	v_add3_u32 v2, s38, v2, v3
	ds_read_b128 v[2:5], v2
	v_lshlrev_b32_e32 v128, 13, v6
	v_lshl_add_u64 v[6:7], v[0:1], 0, v[128:129]
	s_waitcnt lgkmcnt(0)
	global_store_dwordx4 v[6:7], v[2:5], off
	v_or_b32_e32 v6, 48, v139
	s_nop 0
	v_lshlrev_b32_e32 v2, 8, v6
	v_add3_u32 v2, s38, v2, v8
	ds_read_b128 v[2:5], v2
	v_lshlrev_b32_e32 v128, 13, v6
	v_lshl_add_u64 v[6:7], v[0:1], 0, v[128:129]
	s_waitcnt lgkmcnt(0)
	global_store_dwordx4 v[6:7], v[2:5], off
	s_nop 1
	v_bitop3_b32 v3, v139, v138, 52 bitop3:0x36
	v_or_b32_e32 v6, 52, v139
	v_lshlrev_b32_e32 v3, 4, v3
	v_lshlrev_b32_e32 v2, 8, v6
	v_and_b32_e32 v3, 0xf0, v3
	v_add3_u32 v2, s38, v2, v3
	ds_read_b128 v[2:5], v2
	v_lshlrev_b32_e32 v128, 13, v6
	v_lshl_add_u64 v[6:7], v[0:1], 0, v[128:129]
	s_waitcnt lgkmcnt(0)
	global_store_dwordx4 v[6:7], v[2:5], off
	s_nop 1
	v_bitop3_b32 v3, v139, v138, 56 bitop3:0x36
	v_or_b32_e32 v6, 56, v139
	v_lshlrev_b32_e32 v3, 4, v3
	v_lshlrev_b32_e32 v2, 8, v6
	v_and_b32_e32 v3, 0xf0, v3
	v_add3_u32 v2, s38, v2, v3
	ds_read_b128 v[2:5], v2
	v_lshlrev_b32_e32 v128, 13, v6
	v_lshl_add_u64 v[6:7], v[0:1], 0, v[128:129]
	s_waitcnt lgkmcnt(0)
	global_store_dwordx4 v[6:7], v[2:5], off
	s_nop 1
	v_bitop3_b32 v4, v139, v138, 60 bitop3:0x36
	v_or_b32_e32 v3, 60, v139
	v_lshlrev_b32_e32 v4, 4, v4
	v_lshlrev_b32_e32 v2, 8, v3
	v_and_b32_e32 v4, 0xf0, v4
	v_add3_u32 v2, s38, v2, v4
	v_lshlrev_b32_e32 v128, 12, v3
	s_branch .LBB0_803

.LBB0_993:
	s_or_b64 exec, exec, s[6:7]
	ds_read_b128 v[212:215], v189 offset:8192
	ds_read_b128 v[216:219], v189 offset:12288
	ds_read_b128 v[220:223], v188 offset:8192
	ds_read_b128 v[224:227], v188 offset:12288
	ds_read_b128 v[228:231], v190 offset:8192
	ds_read_b128 v[232:235], v190 offset:12288
	ds_read_b128 v[236:239], v191 offset:8192
	ds_read_b128 v[240:243], v191 offset:12288
	v_add_u32_e32 v144, 0x7f, v144
	v_add_u32_e32 v192, s86, v173
	v_cmp_lt_i32_e64 s[14:15], v144, v139
	s_mov_b64 s[6:7], 0
	s_and_saveexec_b64 s[38:39], vcc
	s_cbranch_execz .LBB0_995
	v_mov_b32_e32 v148, 0x42fc0000
	s_cmp_eq_u64 s[14:15], exec
	s_cbranch_scc1 .Lsb_nmA
	s_nop 4
	v_min_f32_e64 v32, -v32, v148
	v_exp_f32_e32 v32, v32
	v_min_f32_e64 v33, -v33, v148
	v_exp_f32_e32 v33, v33
	v_add_f32_e32 v144, 1.0, v32
	v_rcp_f32_e32 v145, v144
	v_add_u32_e32 v144, 0x60, v192
	v_cmp_lt_i32_e64 s[18:19], v144, v187
	v_add_f32_e32 v144, 1.0, v33
	v_rcp_f32_e32 v146, v144
	v_mul_f32_e32 v32, v32, v145
	s_or_b64 s[18:19], s[14:15], s[18:19]
	v_cndmask_b32_e64 v144, 1.0, v32, s[18:19]
	v_mul_f32_e32 v32, v33, v146
	v_add_u32_e32 v33, 0x61, v192
	v_cndmask_b32_e64 v193, 0, v145, s[18:19]
	v_cmp_lt_i32_e64 s[18:19], v33, v187
	v_min_f32_e64 v33, -v34, v148
	v_exp_f32_e32 v33, v33
	v_min_f32_e64 v35, -v35, v148
	v_exp_f32_e32 v35, v35
	v_add_f32_e32 v34, 1.0, v33
	v_rcp_f32_e32 v34, v34
	s_or_b64 s[18:19], s[14:15], s[18:19]
	v_add_u32_e32 v145, 0x62, v192
	v_cndmask_b32_e64 v32, 1.0, v32, s[18:19]
	v_cndmask_b32_e64 v194, 0, v146, s[18:19]
	v_cmp_lt_i32_e64 s[18:19], v145, v187
	v_add_f32_e32 v145, 1.0, v35
	v_rcp_f32_e32 v145, v145
	s_or_b64 s[18:19], s[14:15], s[18:19]
	v_mul_f32_e32 v33, v33, v34
	v_cndmask_b32_e64 v195, 0, v34, s[18:19]
	v_add_u32_e32 v34, 0x63, v192
	v_cndmask_b32_e64 v146, 1.0, v33, s[18:19]
	v_cmp_lt_i32_e64 s[18:19], v34, v187
	v_min_f32_e64 v34, -v36, v148
	v_min_f32_e64 v36, -v37, v148
	v_mul_f32_e32 v33, v35, v145
	v_exp_f32_e32 v35, v34
	v_exp_f32_e32 v36, v36
	s_or_b64 s[18:19], s[14:15], s[18:19]
	v_add_u32_e32 v37, 0x68, v192
	v_cndmask_b32_e64 v34, 1.0, v33, s[18:19]
	v_cndmask_b32_e64 v196, 0, v145, s[18:19]
	v_add_f32_e32 v33, 1.0, v35
	v_cmp_lt_i32_e64 s[18:19], v37, v187
	v_add_f32_e32 v37, 1.0, v36
	v_rcp_f32_e32 v33, v33
	v_rcp_f32_e32 v37, v37
	s_or_b64 s[18:19], s[14:15], s[18:19]
	v_mul_f32_e32 v35, v35, v33
	v_cndmask_b32_e64 v197, 0, v33, s[18:19]
	v_mul_f32_e32 v33, v36, v37
	v_add_u32_e32 v36, 0x69, v192
	v_cndmask_b32_e64 v35, 1.0, v35, s[18:19]
	v_cmp_lt_i32_e64 s[18:19], v36, v187
	v_min_f32_e64 v36, -v38, v148
	s_or_b64 s[18:19], s[14:15], s[18:19]
	v_exp_f32_e32 v36, v36
	v_cndmask_b32_e64 v199, 0, v37, s[18:19]
	v_min_f32_e64 v37, -v39, v148
	v_exp_f32_e32 v37, v37
	v_cndmask_b32_e64 v198, 1.0, v33, s[18:19]
	v_add_f32_e32 v33, 1.0, v36
	v_rcp_f32_e32 v33, v33
	v_add_u32_e32 v38, 0x6a, v192
	v_cmp_lt_i32_e64 s[18:19], v38, v187
	v_add_f32_e32 v38, 1.0, v37
	v_rcp_f32_e32 v38, v38
	v_mul_f32_e32 v36, v36, v33
	s_or_b64 s[18:19], s[14:15], s[18:19]
	v_cndmask_b32_e64 v200, 1.0, v36, s[18:19]
	v_add_u32_e32 v36, 0x6b, v192
	v_cndmask_b32_e64 v201, 0, v33, s[18:19]
	v_mul_f32_e32 v33, v37, v38
	v_cmp_lt_i32_e64 s[18:19], v36, v187
	v_min_f32_e64 v36, -v40, v148
	v_min_f32_e64 v37, -v41, v148
	v_exp_f32_e32 v36, v36
	v_exp_f32_e32 v37, v37
	s_or_b64 s[18:19], s[14:15], s[18:19]
	v_cndmask_b32_e64 v203, 0, v38, s[18:19]
	v_add_u32_e32 v38, 0x70, v192
	v_cndmask_b32_e64 v202, 1.0, v33, s[18:19]
	v_add_f32_e32 v33, 1.0, v36
	v_cmp_lt_i32_e64 s[18:19], v38, v187
	v_add_f32_e32 v38, 1.0, v37
	v_rcp_f32_e32 v33, v33
	v_rcp_f32_e32 v38, v38
	s_or_b64 s[18:19], s[14:15], s[18:19]
	v_min_f32_e64 v41, -v43, v148
	v_mul_f32_e32 v36, v36, v33
	v_cndmask_b32_e64 v39, 0, v33, s[18:19]
	v_mul_f32_e32 v33, v37, v38
	v_add_u32_e32 v37, 0x71, v192
	v_cndmask_b32_e64 v36, 1.0, v36, s[18:19]
	v_cmp_lt_i32_e64 s[18:19], v37, v187
	v_min_f32_e64 v37, -v42, v148
	v_exp_f32_e32 v37, v37
	v_exp_f32_e32 v41, v41
	s_or_b64 s[18:19], s[14:15], s[18:19]
	v_add_u32_e32 v42, 0x72, v192
	v_cndmask_b32_e64 v40, 1.0, v33, s[18:19]
	v_cndmask_b32_e64 v38, 0, v38, s[18:19]
	v_add_f32_e32 v33, 1.0, v37
	v_cmp_lt_i32_e64 s[18:19], v42, v187
	v_add_f32_e32 v42, 1.0, v41
	v_rcp_f32_e32 v33, v33
	v_rcp_f32_e32 v42, v42
	s_or_b64 s[18:19], s[14:15], s[18:19]
	v_min_f32_e64 v43, -v45, v148
	v_mul_f32_e32 v37, v37, v33
	v_cndmask_b32_e64 v204, 0, v33, s[18:19]
	v_mul_f32_e32 v33, v41, v42
	v_add_u32_e32 v41, 0x73, v192
	v_cndmask_b32_e64 v37, 1.0, v37, s[18:19]
	v_cmp_lt_i32_e64 s[18:19], v41, v187
	v_min_f32_e64 v41, -v44, v148
	v_exp_f32_e32 v41, v41
	v_exp_f32_e32 v43, v43
	s_or_b64 s[18:19], s[14:15], s[18:19]
	v_add_u32_e32 v44, 0x78, v192
	v_cndmask_b32_e64 v205, 1.0, v33, s[18:19]
	v_cndmask_b32_e64 v42, 0, v42, s[18:19]
	v_add_f32_e32 v33, 1.0, v41
	v_cmp_lt_i32_e64 s[18:19], v44, v187
	v_add_f32_e32 v44, 1.0, v43
	v_rcp_f32_e32 v33, v33
	v_rcp_f32_e32 v44, v44
	s_or_b64 s[18:19], s[14:15], s[18:19]
	v_min_f32_e64 v45, -v47, v148
	v_mul_f32_e32 v41, v41, v33
	v_cndmask_b32_e64 v206, 0, v33, s[18:19]
	v_mul_f32_e32 v33, v43, v44
	v_add_u32_e32 v43, 0x79, v192
	v_cndmask_b32_e64 v41, 1.0, v41, s[18:19]
	v_cmp_lt_i32_e64 s[18:19], v43, v187
	v_min_f32_e64 v43, -v46, v148
	v_exp_f32_e32 v43, v43
	v_exp_f32_e32 v45, v45
	s_or_b64 s[18:19], s[14:15], s[18:19]
	v_add_u32_e32 v46, 0x7a, v192
	v_cndmask_b32_e64 v207, 1.0, v33, s[18:19]
	v_cndmask_b32_e64 v44, 0, v44, s[18:19]
	v_add_f32_e32 v33, 1.0, v43
	v_cmp_lt_i32_e64 s[18:19], v46, v187
	v_add_f32_e32 v46, 1.0, v45
	v_rcp_f32_e32 v33, v33
	v_rcp_f32_e32 v46, v46
	s_or_b64 s[18:19], s[14:15], s[18:19]
	v_and_b32_e32 v47, 64, v172
	v_mul_f32_e32 v43, v43, v33
	v_cndmask_b32_e64 v208, 0, v33, s[18:19]
	v_mul_f32_e32 v33, v45, v46
	v_add_u32_e32 v45, 0x7b, v192
	v_cndmask_b32_e64 v43, 1.0, v43, s[18:19]
	v_cmp_lt_i32_e64 s[18:19], v45, v187
	s_or_b64 s[18:19], s[14:15], s[18:19]
	v_add_u32_e32 v47, 64, v47
	v_cndmask_b32_e64 v45, 1.0, v33, s[18:19]
	v_xor_b32_e32 v33, 32, v172
	v_cndmask_b32_e64 v46, 0, v46, s[18:19]
	v_cmp_lt_i32_e64 s[18:19], v33, v47
	v_mul_f32_e32 v36, v36, v40
	v_mul_f32_e32 v47, v37, v205
	v_cndmask_b32_e64 v33, v172, v33, s[18:19]
	v_lshlrev_b32_e32 v209, 2, v33
	v_mul_f32_e32 v33, v35, v198
	v_mul_f32_e32 v35, v200, v202
	v_mul_f32_e32 v145, v33, v35
	v_mul_f32_e32 v35, v41, v207
	v_mul_f32_e32 v41, v43, v45
	v_mul_f32_e32 v35, v35, v41

.LBB0_1002:
	v_mov_b32_e32 v148, 0x42fc0000
	s_cmp_eq_u64 s[14:15], exec
	s_cbranch_scc1 .Lsb_nmB
	v_min_f32_e64 v48, -v48, v148
	v_exp_f32_e32 v48, v48
	v_min_f32_e64 v49, -v49, v148
	v_exp_f32_e32 v49, v49
	v_add_f32_e32 v144, 1.0, v48
	v_rcp_f32_e32 v145, v144
	v_add_u32_e32 v144, 64, v192
	v_cmp_lt_i32_e64 s[18:19], v144, v187
	v_add_f32_e32 v144, 1.0, v49
	v_rcp_f32_e32 v146, v144
	v_mul_f32_e32 v48, v48, v145
	s_or_b64 s[18:19], s[14:15], s[18:19]
	v_cndmask_b32_e64 v144, 1.0, v48, s[18:19]
	v_mul_f32_e32 v48, v49, v146
	v_add_u32_e32 v49, 0x41, v192
	v_cndmask_b32_e64 v193, 0, v145, s[18:19]
	v_cmp_lt_i32_e64 s[18:19], v49, v187
	v_min_f32_e64 v49, -v50, v148
	v_exp_f32_e32 v49, v49
	v_min_f32_e64 v51, -v51, v148
	v_exp_f32_e32 v51, v51
	v_add_f32_e32 v50, 1.0, v49
	v_rcp_f32_e32 v50, v50
	s_or_b64 s[18:19], s[14:15], s[18:19]
	v_add_u32_e32 v145, 0x42, v192
	v_cndmask_b32_e64 v48, 1.0, v48, s[18:19]
	v_cndmask_b32_e64 v194, 0, v146, s[18:19]
	v_cmp_lt_i32_e64 s[18:19], v145, v187
	v_add_f32_e32 v145, 1.0, v51
	v_rcp_f32_e32 v145, v145
	s_or_b64 s[18:19], s[14:15], s[18:19]
	v_mul_f32_e32 v49, v49, v50
	v_cndmask_b32_e64 v195, 0, v50, s[18:19]
	v_add_u32_e32 v50, 0x43, v192
	v_cndmask_b32_e64 v146, 1.0, v49, s[18:19]
	v_cmp_lt_i32_e64 s[18:19], v50, v187
	v_min_f32_e64 v50, -v52, v148
	v_min_f32_e64 v52, -v53, v148
	v_mul_f32_e32 v49, v51, v145
	v_exp_f32_e32 v51, v50
	v_exp_f32_e32 v52, v52
	s_or_b64 s[18:19], s[14:15], s[18:19]
	v_add_u32_e32 v53, 0x48, v192
	v_cndmask_b32_e64 v50, 1.0, v49, s[18:19]
	v_cndmask_b32_e64 v196, 0, v145, s[18:19]
	v_add_f32_e32 v49, 1.0, v51
	v_cmp_lt_i32_e64 s[18:19], v53, v187
	v_add_f32_e32 v53, 1.0, v52
	v_rcp_f32_e32 v49, v49
	v_rcp_f32_e32 v53, v53
	s_or_b64 s[18:19], s[14:15], s[18:19]
	v_mul_f32_e32 v51, v51, v49
	v_cndmask_b32_e64 v197, 0, v49, s[18:19]
	v_mul_f32_e32 v49, v52, v53
	v_add_u32_e32 v52, 0x49, v192
	v_cndmask_b32_e64 v51, 1.0, v51, s[18:19]
	v_cmp_lt_i32_e64 s[18:19], v52, v187
	v_min_f32_e64 v52, -v54, v148
	s_or_b64 s[18:19], s[14:15], s[18:19]
	v_exp_f32_e32 v52, v52
	v_cndmask_b32_e64 v199, 0, v53, s[18:19]
	v_min_f32_e64 v53, -v55, v148
	v_exp_f32_e32 v53, v53
	v_cndmask_b32_e64 v198, 1.0, v49, s[18:19]
	v_add_f32_e32 v49, 1.0, v52
	v_rcp_f32_e32 v49, v49
	v_add_u32_e32 v54, 0x4a, v192
	v_cmp_lt_i32_e64 s[18:19], v54, v187
	v_add_f32_e32 v54, 1.0, v53
	v_rcp_f32_e32 v54, v54
	v_mul_f32_e32 v52, v52, v49
	s_or_b64 s[18:19], s[14:15], s[18:19]
	v_cndmask_b32_e64 v200, 1.0, v52, s[18:19]
	v_add_u32_e32 v52, 0x4b, v192
	v_cndmask_b32_e64 v201, 0, v49, s[18:19]
	v_mul_f32_e32 v49, v53, v54
	v_cmp_lt_i32_e64 s[18:19], v52, v187
	v_min_f32_e64 v52, -v56, v148
	v_min_f32_e64 v53, -v57, v148
	v_exp_f32_e32 v52, v52
	v_exp_f32_e32 v53, v53
	s_or_b64 s[18:19], s[14:15], s[18:19]
	v_cndmask_b32_e64 v203, 0, v54, s[18:19]
	v_add_u32_e32 v54, 0x50, v192
	v_cndmask_b32_e64 v202, 1.0, v49, s[18:19]
	v_add_f32_e32 v49, 1.0, v52
	v_cmp_lt_i32_e64 s[18:19], v54, v187
	v_add_f32_e32 v54, 1.0, v53
	v_rcp_f32_e32 v49, v49
	v_rcp_f32_e32 v54, v54
	s_or_b64 s[18:19], s[14:15], s[18:19]
	v_min_f32_e64 v57, -v59, v148
	v_mul_f32_e32 v52, v52, v49
	v_cndmask_b32_e64 v55, 0, v49, s[18:19]
	v_mul_f32_e32 v49, v53, v54
	v_add_u32_e32 v53, 0x51, v192
	v_cndmask_b32_e64 v52, 1.0, v52, s[18:19]
	v_cmp_lt_i32_e64 s[18:19], v53, v187
	v_min_f32_e64 v53, -v58, v148
	v_exp_f32_e32 v53, v53
	v_exp_f32_e32 v57, v57
	s_or_b64 s[18:19], s[14:15], s[18:19]
	v_add_u32_e32 v58, 0x52, v192
	v_cndmask_b32_e64 v56, 1.0, v49, s[18:19]
	v_cndmask_b32_e64 v54, 0, v54, s[18:19]
	v_add_f32_e32 v49, 1.0, v53
	v_cmp_lt_i32_e64 s[18:19], v58, v187
	v_add_f32_e32 v58, 1.0, v57
	v_rcp_f32_e32 v49, v49
	v_rcp_f32_e32 v58, v58
	s_or_b64 s[18:19], s[14:15], s[18:19]
	v_min_f32_e64 v59, -v61, v148
	v_mul_f32_e32 v53, v53, v49
	v_cndmask_b32_e64 v204, 0, v49, s[18:19]
	v_mul_f32_e32 v49, v57, v58
	v_add_u32_e32 v57, 0x53, v192
	v_cndmask_b32_e64 v53, 1.0, v53, s[18:19]
	v_cmp_lt_i32_e64 s[18:19], v57, v187
	v_min_f32_e64 v57, -v60, v148
	v_exp_f32_e32 v57, v57
	v_exp_f32_e32 v59, v59
	s_or_b64 s[18:19], s[14:15], s[18:19]
	v_add_u32_e32 v60, 0x58, v192
	v_cndmask_b32_e64 v205, 1.0, v49, s[18:19]
	v_cndmask_b32_e64 v58, 0, v58, s[18:19]
	v_add_f32_e32 v49, 1.0, v57
	v_cmp_lt_i32_e64 s[18:19], v60, v187
	v_add_f32_e32 v60, 1.0, v59
	v_rcp_f32_e32 v49, v49
	v_rcp_f32_e32 v60, v60
	s_or_b64 s[18:19], s[14:15], s[18:19]
	v_min_f32_e64 v61, -v63, v148
	v_mul_f32_e32 v57, v57, v49
	v_cndmask_b32_e64 v206, 0, v49, s[18:19]
	v_mul_f32_e32 v49, v59, v60
	v_add_u32_e32 v59, 0x59, v192
	v_cndmask_b32_e64 v57, 1.0, v57, s[18:19]
	v_cmp_lt_i32_e64 s[18:19], v59, v187
	v_min_f32_e64 v59, -v62, v148
	v_exp_f32_e32 v59, v59
	v_exp_f32_e32 v61, v61
	s_or_b64 s[18:19], s[14:15], s[18:19]
	v_add_u32_e32 v62, 0x5a, v192
	v_cndmask_b32_e64 v207, 1.0, v49, s[18:19]
	v_cndmask_b32_e64 v60, 0, v60, s[18:19]
	v_add_f32_e32 v49, 1.0, v59
	v_cmp_lt_i32_e64 s[18:19], v62, v187
	v_add_f32_e32 v62, 1.0, v61
	v_rcp_f32_e32 v49, v49
	v_rcp_f32_e32 v62, v62
	s_or_b64 s[18:19], s[14:15], s[18:19]
	v_and_b32_e32 v63, 64, v172
	v_mul_f32_e32 v59, v59, v49
	v_cndmask_b32_e64 v208, 0, v49, s[18:19]
	v_mul_f32_e32 v49, v61, v62
	v_add_u32_e32 v61, 0x5b, v192
	v_cndmask_b32_e64 v59, 1.0, v59, s[18:19]
	v_cmp_lt_i32_e64 s[18:19], v61, v187
	s_or_b64 s[14:15], s[14:15], s[18:19]
	v_cndmask_b32_e64 v61, 1.0, v49, s[14:15]
	v_xor_b32_e32 v49, 32, v172
	v_add_u32_e32 v63, 64, v63
	v_cndmask_b32_e64 v62, 0, v62, s[14:15]
	v_cmp_lt_i32_e64 s[14:15], v49, v63
	v_mul_f32_e32 v52, v52, v56
	v_mul_f32_e32 v63, v53, v205
	v_cndmask_b32_e64 v49, v172, v49, s[14:15]
	v_lshlrev_b32_e32 v192, 2, v49
	v_mul_f32_e32 v49, v51, v198
	v_mul_f32_e32 v51, v200, v202
	v_mul_f32_e32 v145, v49, v51
	v_mul_f32_e32 v51, v57, v207
	v_mul_f32_e32 v57, v59, v61
	v_mul_f32_e32 v51, v51, v57

.Lsb_nmA:
	s_nop 4
	v_min_f32_e64 v32, -v32, v148
	v_exp_f32_e32 v32, v32
	v_min_f32_e64 v33, -v33, v148
	v_exp_f32_e32 v33, v33
	v_add_f32_e32 v144, 1.0, v32
	v_rcp_f32_e32 v145, v144
	v_add_f32_e32 v144, 1.0, v33
	v_rcp_f32_e32 v146, v144
	v_mul_f32_e32 v32, v32, v145
	v_mov_b32_e32 v144, v32
	v_mul_f32_e32 v32, v33, v146
	v_mov_b32_e32 v193, v145
	v_min_f32_e64 v33, -v34, v148
	v_exp_f32_e32 v33, v33
	v_min_f32_e64 v35, -v35, v148
	v_exp_f32_e32 v35, v35
	v_add_f32_e32 v34, 1.0, v33
	v_rcp_f32_e32 v34, v34
	v_mov_b32_e32 v194, v146
	v_add_f32_e32 v145, 1.0, v35
	v_rcp_f32_e32 v145, v145
	v_mul_f32_e32 v33, v33, v34
	v_mov_b32_e32 v195, v34
	v_mov_b32_e32 v146, v33
	v_min_f32_e64 v34, -v36, v148
	v_min_f32_e64 v36, -v37, v148
	v_mul_f32_e32 v33, v35, v145
	v_exp_f32_e32 v35, v34
	v_exp_f32_e32 v36, v36
	v_mov_b32_e32 v34, v33
	v_mov_b32_e32 v196, v145
	v_add_f32_e32 v33, 1.0, v35
	v_add_f32_e32 v37, 1.0, v36
	v_rcp_f32_e32 v33, v33
	v_rcp_f32_e32 v37, v37
	v_mul_f32_e32 v35, v35, v33
	v_mov_b32_e32 v197, v33
	v_mul_f32_e32 v33, v36, v37
	v_min_f32_e64 v36, -v38, v148
	v_exp_f32_e32 v36, v36
	v_mov_b32_e32 v199, v37
	v_min_f32_e64 v37, -v39, v148
	v_exp_f32_e32 v37, v37
	v_mov_b32_e32 v198, v33
	v_add_f32_e32 v33, 1.0, v36
	v_rcp_f32_e32 v33, v33
	v_add_f32_e32 v38, 1.0, v37
	v_rcp_f32_e32 v38, v38
	v_mul_f32_e32 v36, v36, v33
	v_mov_b32_e32 v200, v36
	v_mov_b32_e32 v201, v33
	v_mul_f32_e32 v33, v37, v38
	v_min_f32_e64 v36, -v40, v148
	v_min_f32_e64 v37, -v41, v148
	v_exp_f32_e32 v36, v36
	v_exp_f32_e32 v37, v37
	v_mov_b32_e32 v203, v38
	v_mov_b32_e32 v202, v33
	v_add_f32_e32 v33, 1.0, v36
	v_add_f32_e32 v38, 1.0, v37
	v_rcp_f32_e32 v33, v33
	v_rcp_f32_e32 v38, v38
	v_min_f32_e64 v41, -v43, v148
	v_mul_f32_e32 v36, v36, v33
	v_mov_b32_e32 v39, v33
	v_mul_f32_e32 v33, v37, v38
	v_min_f32_e64 v37, -v42, v148
	v_exp_f32_e32 v37, v37
	v_exp_f32_e32 v41, v41
	v_mov_b32_e32 v40, v33
	v_add_f32_e32 v33, 1.0, v37
	v_add_f32_e32 v42, 1.0, v41
	v_rcp_f32_e32 v33, v33
	v_rcp_f32_e32 v42, v42
	v_min_f32_e64 v43, -v45, v148
	v_mul_f32_e32 v37, v37, v33
	v_mov_b32_e32 v204, v33
	v_mul_f32_e32 v33, v41, v42
	v_min_f32_e64 v41, -v44, v148
	v_exp_f32_e32 v41, v41
	v_exp_f32_e32 v43, v43
	v_mov_b32_e32 v205, v33
	v_add_f32_e32 v33, 1.0, v41
	v_add_f32_e32 v44, 1.0, v43
	v_rcp_f32_e32 v33, v33
	v_rcp_f32_e32 v44, v44
	v_min_f32_e64 v45, -v47, v148
	v_mul_f32_e32 v41, v41, v33
	v_mov_b32_e32 v206, v33
	v_mul_f32_e32 v33, v43, v44
	v_min_f32_e64 v43, -v46, v148
	v_exp_f32_e32 v43, v43
	v_exp_f32_e32 v45, v45
	v_mov_b32_e32 v207, v33
	v_add_f32_e32 v33, 1.0, v43
	v_add_f32_e32 v46, 1.0, v45
	v_rcp_f32_e32 v33, v33
	v_rcp_f32_e32 v46, v46
	v_and_b32_e32 v47, 64, v172
	v_mul_f32_e32 v43, v43, v33
	v_mov_b32_e32 v208, v33
	v_mul_f32_e32 v33, v45, v46
	v_add_u32_e32 v47, 64, v47
	v_mov_b32_e32 v45, v33
	v_xor_b32_e32 v33, 32, v172
	v_cmp_lt_i32_e64 s[18:19], v33, v47
	v_mul_f32_e32 v36, v36, v40
	v_mul_f32_e32 v47, v37, v205
	v_cndmask_b32_e64 v33, v172, v33, s[18:19]
	v_lshlrev_b32_e32 v209, 2, v33
	v_mul_f32_e32 v33, v35, v198
	v_mul_f32_e32 v35, v200, v202
	v_mul_f32_e32 v145, v33, v35
	v_mul_f32_e32 v35, v41, v207
	v_mul_f32_e32 v41, v43, v45
	v_mul_f32_e32 v35, v35, v41
	s_branch .Lsb_joinA
.Lsb_nmB:
	v_min_f32_e64 v48, -v48, v148
	v_exp_f32_e32 v48, v48
	v_min_f32_e64 v49, -v49, v148
	v_exp_f32_e32 v49, v49
	v_add_f32_e32 v144, 1.0, v48
	v_rcp_f32_e32 v145, v144
	v_add_f32_e32 v144, 1.0, v49
	v_rcp_f32_e32 v146, v144
	v_mul_f32_e32 v48, v48, v145
	v_mov_b32_e32 v144, v48
	v_mul_f32_e32 v48, v49, v146
	v_mov_b32_e32 v193, v145
	v_min_f32_e64 v49, -v50, v148
	v_exp_f32_e32 v49, v49
	v_min_f32_e64 v51, -v51, v148
	v_exp_f32_e32 v51, v51
	v_add_f32_e32 v50, 1.0, v49
	v_rcp_f32_e32 v50, v50
	v_mov_b32_e32 v194, v146
	v_add_f32_e32 v145, 1.0, v51
	v_rcp_f32_e32 v145, v145
	v_mul_f32_e32 v49, v49, v50
	v_mov_b32_e32 v195, v50
	v_mov_b32_e32 v146, v49
	v_min_f32_e64 v50, -v52, v148
	v_min_f32_e64 v52, -v53, v148
	v_mul_f32_e32 v49, v51, v145
	v_exp_f32_e32 v51, v50
	v_exp_f32_e32 v52, v52
	v_mov_b32_e32 v50, v49
	v_mov_b32_e32 v196, v145
	v_add_f32_e32 v49, 1.0, v51
	v_add_f32_e32 v53, 1.0, v52
	v_rcp_f32_e32 v49, v49
	v_rcp_f32_e32 v53, v53
	v_mul_f32_e32 v51, v51, v49
	v_mov_b32_e32 v197, v49
	v_mul_f32_e32 v49, v52, v53
	v_min_f32_e64 v52, -v54, v148
	v_exp_f32_e32 v52, v52
	v_mov_b32_e32 v199, v53
	v_min_f32_e64 v53, -v55, v148
	v_exp_f32_e32 v53, v53
	v_mov_b32_e32 v198, v49
	v_add_f32_e32 v49, 1.0, v52
	v_rcp_f32_e32 v49, v49
	v_add_f32_e32 v54, 1.0, v53
	v_rcp_f32_e32 v54, v54
	v_mul_f32_e32 v52, v52, v49
	v_mov_b32_e32 v200, v52
	v_mov_b32_e32 v201, v49
	v_mul_f32_e32 v49, v53, v54
	v_min_f32_e64 v52, -v56, v148
	v_min_f32_e64 v53, -v57, v148
	v_exp_f32_e32 v52, v52
	v_exp_f32_e32 v53, v53
	v_mov_b32_e32 v203, v54
	v_mov_b32_e32 v202, v49
	v_add_f32_e32 v49, 1.0, v52
	v_add_f32_e32 v54, 1.0, v53
	v_rcp_f32_e32 v49, v49
	v_rcp_f32_e32 v54, v54
	v_min_f32_e64 v57, -v59, v148
	v_mul_f32_e32 v52, v52, v49
	v_mov_b32_e32 v55, v49
	v_mul_f32_e32 v49, v53, v54
	v_min_f32_e64 v53, -v58, v148
	v_exp_f32_e32 v53, v53
	v_exp_f32_e32 v57, v57
	v_mov_b32_e32 v56, v49
	v_add_f32_e32 v49, 1.0, v53
	v_add_f32_e32 v58, 1.0, v57
	v_rcp_f32_e32 v49, v49
	v_rcp_f32_e32 v58, v58
	v_min_f32_e64 v59, -v61, v148
	v_mul_f32_e32 v53, v53, v49
	v_mov_b32_e32 v204, v49
	v_mul_f32_e32 v49, v57, v58
	v_min_f32_e64 v57, -v60, v148
	v_exp_f32_e32 v57, v57
	v_exp_f32_e32 v59, v59
	v_mov_b32_e32 v205, v49
	v_add_f32_e32 v49, 1.0, v57
	v_add_f32_e32 v60, 1.0, v59
	v_rcp_f32_e32 v49, v49
	v_rcp_f32_e32 v60, v60
	v_min_f32_e64 v61, -v63, v148
	v_mul_f32_e32 v57, v57, v49
	v_mov_b32_e32 v206, v49
	v_mul_f32_e32 v49, v59, v60
	v_min_f32_e64 v59, -v62, v148
	v_exp_f32_e32 v59, v59
	v_exp_f32_e32 v61, v61
	v_mov_b32_e32 v207, v49
	v_add_f32_e32 v49, 1.0, v59
	v_add_f32_e32 v62, 1.0, v61
	v_rcp_f32_e32 v49, v49
	v_rcp_f32_e32 v62, v62
	v_and_b32_e32 v63, 64, v172
	v_mul_f32_e32 v59, v59, v49
	v_mov_b32_e32 v208, v49
	v_mul_f32_e32 v49, v61, v62
	v_mov_b32_e32 v61, v49
	v_xor_b32_e32 v49, 32, v172
	v_add_u32_e32 v63, 64, v63
	v_cmp_lt_i32_e64 s[14:15], v49, v63
	v_mul_f32_e32 v52, v52, v56
	v_mul_f32_e32 v63, v53, v205
	v_cndmask_b32_e64 v49, v172, v49, s[14:15]
	v_lshlrev_b32_e32 v192, 2, v49
	v_mul_f32_e32 v49, v51, v198
	v_mul_f32_e32 v51, v200, v202
	v_mul_f32_e32 v145, v49, v51
	v_mul_f32_e32 v51, v57, v207
	v_mul_f32_e32 v57, v59, v61
	v_mul_f32_e32 v51, v51, v57
	s_branch .Lsb_joinB

.Lgsk4_loop:
	s_add_i32 s9, s8, 0xfffe8000
	s_and_b32 s10, s8, 0x18000
	s_and_b32 s9, s9, 0x18000
	s_add_i32 s10, s7, s10
	v_add_u32_e32 v128, s9, v139
	v_or_b32_e32 v141, s9, v140
	s_add_i32 s15, s10, 0x400
	s_add_i32 s11, s10, 0x800
	s_add_i32 s9, s10, 0xc00
	s_add_i32 s8, s8, 0x8000
	s_cmp_eq_u32 s8, 0x100000
	s_waitcnt vmcnt(8) lgkmcnt(0)
	s_barrier
	v_mfma_f32_16x16x32_bf16 v[60:63], v[142:145], v[232:235], v[60:63]
	ds_read_b128 v[174:177], v128
	ds_read_b128 v[178:181], v128 offset:1024
	v_mfma_f32_16x16x32_bf16 v[44:47], v[142:145], v[236:239], v[44:47]
	ds_read_b128 v[182:185], v128 offset:2048
	ds_read_b128 v[186:189], v128 offset:3072
	v_mfma_f32_16x16x32_bf16 v[28:31], v[142:145], v[240:243], v[28:31]
	s_mov_b32 m0, s10
	v_mfma_f32_16x16x32_bf16 v[12:15], v[142:145], v[244:247], v[12:15]
	global_load_lds_dwordx4 v[136:137], off
	v_lshl_add_u64 v[136:137], v[136:137], 0, 64
	v_mfma_f32_16x16x32_bf16 v[56:59], v[158:161], v[232:235], v[56:59]
	ds_read_b128 v[142:145], v141
	v_mfma_f32_16x16x32_bf16 v[40:43], v[158:161], v[236:239], v[40:43]
	v_mfma_f32_16x16x32_bf16 v[24:27], v[158:161], v[240:243], v[24:27]
	s_mov_b32 m0, s15
	v_mfma_f32_16x16x32_bf16 v[8:11], v[158:161], v[244:247], v[8:11]
	global_load_lds_dwordx4 v[134:135], off
	v_lshl_add_u64 v[134:135], v[134:135], 0, 64
	v_mfma_f32_16x16x32_bf16 v[52:55], v[162:165], v[232:235], v[52:55]
	ds_read_b128 v[158:161], v141 offset:1024
	v_mfma_f32_16x16x32_bf16 v[36:39], v[162:165], v[236:239], v[36:39]
	v_mfma_f32_16x16x32_bf16 v[20:23], v[162:165], v[240:243], v[20:23]
	s_mov_b32 m0, s11
	v_mfma_f32_16x16x32_bf16 v[4:7], v[162:165], v[244:247], v[4:7]
	global_load_lds_dwordx4 v[132:133], off
	v_lshl_add_u64 v[132:133], v[132:133], 0, 64
	v_mfma_f32_16x16x32_bf16 v[48:51], v[166:169], v[232:235], v[48:51]
	ds_read_b128 v[162:165], v141 offset:2048
	v_mfma_f32_16x16x32_bf16 v[32:35], v[166:169], v[236:239], v[32:35]
	v_mfma_f32_16x16x32_bf16 v[16:19], v[166:169], v[240:243], v[16:19]
	s_mov_b32 m0, s9
	v_mfma_f32_16x16x32_bf16 v[0:3], v[166:169], v[244:247], v[0:3]
	global_load_lds_dwordx4 v[130:131], off
	v_lshl_add_u64 v[130:131], v[130:131], 0, 64
	s_waitcnt lgkmcnt(2)
	v_mfma_f32_16x16x32_bf16 v[124:127], v[142:145], v[174:177], v[124:127]
	ds_read_b128 v[166:169], v141 offset:3072
	v_mfma_f32_16x16x32_bf16 v[108:111], v[142:145], v[178:181], v[108:111]
	ds_read_b128 v[232:235], v128 offset:4096
	ds_read_b128 v[236:239], v128 offset:5120
	v_mfma_f32_16x16x32_bf16 v[92:95], v[142:145], v[182:185], v[92:95]
	ds_read_b128 v[240:243], v128 offset:6144
	ds_read_b128 v[244:247], v128 offset:7168
	v_mfma_f32_16x16x32_bf16 v[76:79], v[142:145], v[186:189], v[76:79]
	s_waitcnt lgkmcnt(6)
	v_mfma_f32_16x16x32_bf16 v[120:123], v[158:161], v[174:177], v[120:123]
	v_mfma_f32_16x16x32_bf16 v[104:107], v[158:161], v[178:181], v[104:107]
	v_mfma_f32_16x16x32_bf16 v[88:91], v[158:161], v[182:185], v[88:91]
	v_mfma_f32_16x16x32_bf16 v[72:75], v[158:161], v[186:189], v[72:75]
	s_waitcnt lgkmcnt(5)
	v_mfma_f32_16x16x32_bf16 v[116:119], v[162:165], v[174:177], v[116:119]
	v_mfma_f32_16x16x32_bf16 v[100:103], v[162:165], v[178:181], v[100:103]
	v_mfma_f32_16x16x32_bf16 v[84:87], v[162:165], v[182:185], v[84:87]
	v_mfma_f32_16x16x32_bf16 v[68:71], v[162:165], v[186:189], v[68:71]
	s_waitcnt lgkmcnt(4)
	v_mfma_f32_16x16x32_bf16 v[112:115], v[166:169], v[174:177], v[112:115]
	v_mfma_f32_16x16x32_bf16 v[96:99], v[166:169], v[178:181], v[96:99]
	v_mfma_f32_16x16x32_bf16 v[80:83], v[166:169], v[182:185], v[80:83]
	v_mfma_f32_16x16x32_bf16 v[64:67], v[166:169], v[186:189], v[64:67]
	s_cbranch_scc0 .Lgsk4_loop
	s_waitcnt lgkmcnt(0)
	v_mfma_f32_16x16x32_bf16 v[60:63], v[142:145], v[232:235], v[60:63]
	v_mfma_f32_16x16x32_bf16 v[44:47], v[142:145], v[236:239], v[44:47]
	v_mfma_f32_16x16x32_bf16 v[28:31], v[142:145], v[240:243], v[28:31]
	v_mfma_f32_16x16x32_bf16 v[12:15], v[142:145], v[244:247], v[12:15]
	v_mfma_f32_16x16x32_bf16 v[56:59], v[158:161], v[232:235], v[56:59]
	v_mfma_f32_16x16x32_bf16 v[40:43], v[158:161], v[236:239], v[40:43]
	v_mfma_f32_16x16x32_bf16 v[24:27], v[158:161], v[240:243], v[24:27]
	v_mfma_f32_16x16x32_bf16 v[8:11], v[158:161], v[244:247], v[8:11]
	v_mfma_f32_16x16x32_bf16 v[52:55], v[162:165], v[232:235], v[52:55]
	v_mfma_f32_16x16x32_bf16 v[36:39], v[162:165], v[236:239], v[36:39]
	v_mfma_f32_16x16x32_bf16 v[20:23], v[162:165], v[240:243], v[20:23]
	v_mfma_f32_16x16x32_bf16 v[4:7], v[162:165], v[244:247], v[4:7]
	v_mfma_f32_16x16x32_bf16 v[48:51], v[166:169], v[232:235], v[48:51]
	v_mfma_f32_16x16x32_bf16 v[32:35], v[166:169], v[236:239], v[32:35]
	v_mfma_f32_16x16x32_bf16 v[16:19], v[166:169], v[240:243], v[16:19]
	v_mfma_f32_16x16x32_bf16 v[0:3], v[166:169], v[244:247], v[0:3]
	s_waitcnt vmcnt(8)
	s_barrier
	v_add_u32_e32 v128, 0x8000, v139
	v_or_b32_e32 v141, 0x8000, v140
	ds_read_b128 v[130:133], v141
	ds_read_b128 v[134:137], v141 offset:1024
	ds_read_b128 v[142:145], v141 offset:2048
	ds_read_b128 v[158:161], v141 offset:3072
	ds_read_b128 v[162:165], v128
	ds_read_b128 v[166:169], v128 offset:1024
	ds_read_b128 v[174:177], v128 offset:2048
	ds_read_b128 v[178:181], v128 offset:3072
	s_lshl_b32 s8, s6, 8
	s_waitcnt lgkmcnt(0)
	s_and_b32 s15, s8, 0xffffc000
	v_mfma_f32_16x16x32_bf16 v[124:127], v[130:133], v[162:165], v[124:127]
	s_ashr_i32 s7, s6, 1
	s_and_b32 s7, s7, 0xffffff80
	s_and_b32 s6, s6, 0xc0
	v_mfma_f32_16x16x32_bf16 v[120:123], v[134:137], v[162:165], v[120:123]
	s_add_i32 s8, s4, s7
	s_or_b32 s4, s5, s6
	s_ashr_i32 s10, s4, 6
	v_mfma_f32_16x16x32_bf16 v[182:185], v[142:145], v[162:165], v[116:119]
	s_ashr_i32 s11, s10, 31
	v_mfma_f32_16x16x32_bf16 v[112:115], v[158:161], v[162:165], v[112:115]
	v_mfma_f32_16x16x32_bf16 v[108:111], v[130:133], v[166:169], v[108:111]
	v_mfma_f32_16x16x32_bf16 v[104:107], v[134:137], v[166:169], v[104:107]
	v_mfma_f32_16x16x32_bf16 v[100:103], v[142:145], v[166:169], v[100:103]
	v_mfma_f32_16x16x32_bf16 v[96:99], v[158:161], v[166:169], v[96:99]
	v_mfma_f32_16x16x32_bf16 v[92:95], v[130:133], v[174:177], v[92:95]
	v_mfma_f32_16x16x32_bf16 v[88:91], v[134:137], v[174:177], v[88:91]
	v_mfma_f32_16x16x32_bf16 v[84:87], v[142:145], v[174:177], v[84:87]
	v_mfma_f32_16x16x32_bf16 v[80:83], v[158:161], v[174:177], v[80:83]
	ds_read_b128 v[116:119], v128 offset:4096
	ds_read_b128 v[162:165], v128 offset:5120
	ds_read_b128 v[166:169], v128 offset:6144
	ds_read_b128 v[174:177], v128 offset:7168
	s_waitcnt lgkmcnt(0)
	s_waitcnt vmcnt(4)
	s_barrier
	v_mfma_f32_16x16x32_bf16 v[76:79], v[130:133], v[178:181], v[76:79]
	v_mfma_f32_16x16x32_bf16 v[72:75], v[134:137], v[178:181], v[72:75]
	v_mfma_f32_16x16x32_bf16 v[68:71], v[142:145], v[178:181], v[68:71]
	v_mfma_f32_16x16x32_bf16 v[64:67], v[158:161], v[178:181], v[64:67]
	v_mfma_f32_16x16x32_bf16 v[60:63], v[130:133], v[116:119], v[60:63]
	v_mfma_f32_16x16x32_bf16 v[56:59], v[134:137], v[116:119], v[56:59]
	v_mfma_f32_16x16x32_bf16 v[52:55], v[142:145], v[116:119], v[52:55]
	v_mfma_f32_16x16x32_bf16 v[48:51], v[158:161], v[116:119], v[48:51]
	v_add_u32_e32 v117, 0x10000, v139
	v_or_b32_e32 v119, 0x10000, v140
	v_and_b32_e32 v116, 15, v138
	v_mfma_f32_16x16x32_bf16 v[44:47], v[130:133], v[162:165], v[44:47]
	v_and_b32_e32 v118, 63, v138
	v_mfma_f32_16x16x32_bf16 v[40:43], v[134:137], v[162:165], v[40:43]
	v_mfma_f32_16x16x32_bf16 v[36:39], v[142:145], v[162:165], v[36:39]
	v_mfma_f32_16x16x32_bf16 v[32:35], v[158:161], v[162:165], v[32:35]
	v_mfma_f32_16x16x32_bf16 v[28:31], v[130:133], v[166:169], v[28:31]
	v_mfma_f32_16x16x32_bf16 v[24:27], v[134:137], v[166:169], v[24:27]
	v_mfma_f32_16x16x32_bf16 v[20:23], v[142:145], v[166:169], v[20:23]
	v_mfma_f32_16x16x32_bf16 v[16:19], v[158:161], v[166:169], v[16:19]
	v_mfma_f32_16x16x32_bf16 v[12:15], v[130:133], v[174:177], v[12:15]
	v_mfma_f32_16x16x32_bf16 v[8:11], v[134:137], v[174:177], v[8:11]
	v_mfma_f32_16x16x32_bf16 v[4:7], v[142:145], v[174:177], v[4:7]
	v_mfma_f32_16x16x32_bf16 v[0:3], v[158:161], v[174:177], v[0:3]
	ds_read_b128 v[130:133], v119
	ds_read_b128 v[134:137], v119 offset:1024
	ds_read_b128 v[142:145], v119 offset:2048
	ds_read_b128 v[158:161], v119 offset:3072
	ds_read_b128 v[162:165], v117
	ds_read_b128 v[166:169], v117 offset:1024
	ds_read_b128 v[174:177], v117 offset:2048
	ds_read_b128 v[178:181], v117 offset:3072
	v_or_b32_e32 v119, 0x18000, v140
	s_waitcnt lgkmcnt(0)
	s_nop 0
	v_mfma_f32_16x16x32_bf16 v[124:127], v[130:133], v[162:165], v[124:127]
	v_mfma_f32_16x16x32_bf16 v[120:123], v[134:137], v[162:165], v[120:123]
	v_mfma_f32_16x16x32_bf16 v[182:185], v[142:145], v[162:165], v[182:185]
	v_mfma_f32_16x16x32_bf16 v[112:115], v[158:161], v[162:165], v[112:115]
	v_mfma_f32_16x16x32_bf16 v[108:111], v[130:133], v[166:169], v[108:111]
	v_mfma_f32_16x16x32_bf16 v[104:107], v[134:137], v[166:169], v[104:107]
	v_mfma_f32_16x16x32_bf16 v[100:103], v[142:145], v[166:169], v[100:103]
	v_mfma_f32_16x16x32_bf16 v[162:165], v[158:161], v[166:169], v[96:99]
	v_mfma_f32_16x16x32_bf16 v[92:95], v[130:133], v[174:177], v[92:95]
	v_mfma_f32_16x16x32_bf16 v[88:91], v[134:137], v[174:177], v[88:91]
	v_mfma_f32_16x16x32_bf16 v[84:87], v[142:145], v[174:177], v[84:87]
	v_mfma_f32_16x16x32_bf16 v[80:83], v[158:161], v[174:177], v[80:83]
	v_mfma_f32_16x16x32_bf16 v[76:79], v[130:133], v[178:181], v[76:79]
	v_mfma_f32_16x16x32_bf16 v[72:75], v[134:137], v[178:181], v[72:75]
	v_mfma_f32_16x16x32_bf16 v[68:71], v[142:145], v[178:181], v[68:71]
	v_mfma_f32_16x16x32_bf16 v[64:67], v[158:161], v[178:181], v[64:67]
	ds_read_b128 v[96:99], v117 offset:4096
	ds_read_b128 v[166:169], v117 offset:5120
	ds_read_b128 v[174:177], v117 offset:6144
	ds_read_b128 v[178:181], v117 offset:7168
	s_waitcnt lgkmcnt(0)
	s_waitcnt vmcnt(0)
	s_barrier
	v_mfma_f32_16x16x32_bf16 v[60:63], v[130:133], v[96:99], v[60:63]
	v_add_u32_e32 v117, 0x18000, v139
	v_mfma_f32_16x16x32_bf16 v[56:59], v[134:137], v[96:99], v[56:59]
	v_mfma_f32_16x16x32_bf16 v[52:55], v[142:145], v[96:99], v[52:55]
	v_mfma_f32_16x16x32_bf16 v[48:51], v[158:161], v[96:99], v[48:51]
	v_mfma_f32_16x16x32_bf16 v[44:47], v[130:133], v[166:169], v[44:47]
	v_mfma_f32_16x16x32_bf16 v[40:43], v[134:137], v[166:169], v[40:43]
	v_mfma_f32_16x16x32_bf16 v[36:39], v[142:145], v[166:169], v[36:39]
	v_mfma_f32_16x16x32_bf16 v[32:35], v[158:161], v[166:169], v[32:35]
	v_mfma_f32_16x16x32_bf16 v[28:31], v[130:133], v[174:177], v[28:31]
	v_mfma_f32_16x16x32_bf16 v[24:27], v[134:137], v[174:177], v[24:27]
	v_mfma_f32_16x16x32_bf16 v[20:23], v[142:145], v[174:177], v[20:23]
	v_mfma_f32_16x16x32_bf16 v[16:19], v[158:161], v[174:177], v[16:19]
	v_mfma_f32_16x16x32_bf16 v[12:15], v[130:133], v[178:181], v[12:15]
	v_mfma_f32_16x16x32_bf16 v[8:11], v[134:137], v[178:181], v[8:11]
	v_mfma_f32_16x16x32_bf16 v[4:7], v[142:145], v[178:181], v[4:7]
	v_mfma_f32_16x16x32_bf16 v[0:3], v[158:161], v[178:181], v[0:3]
	ds_read_b128 v[130:133], v119
	ds_read_b128 v[134:137], v119 offset:1024
	ds_read_b128 v[140:143], v119 offset:2048
	ds_read_b128 v[144:147], v119 offset:3072
	ds_read_b128 v[96:99], v117
	ds_read_b128 v[158:161], v117 offset:1024
	ds_read_b128 v[166:169], v117 offset:2048
	ds_read_b128 v[174:177], v117 offset:3072
	v_and_b32_e32 v119, 7, v138
	s_waitcnt lgkmcnt(0)
	s_nop 0
	v_mfma_f32_16x16x32_bf16 v[124:127], v[130:133], v[96:99], v[124:127]
	v_mfma_f32_16x16x32_bf16 v[178:181], v[134:137], v[96:99], v[120:123]
	v_mfma_f32_16x16x32_bf16 v[182:185], v[140:143], v[96:99], v[182:185]
	s_nop 5
	v_mul_f32_e32 v128, v125, v125
	v_fmac_f32_e32 v128, v124, v124
	v_fmac_f32_e32 v128, v126, v126
	v_mfma_f32_16x16x32_bf16 v[112:115], v[144:147], v[96:99], v[112:115]
	v_cvt_pk_bf16_f32 v124, v124, v125
	v_cvt_pk_bf16_f32 v125, v126, v127
	v_fmac_f32_e32 v128, v127, v127
	v_mfma_f32_16x16x32_bf16 v[108:111], v[130:133], v[158:161], v[108:111]
	v_cvt_pk_bf16_f32 v127, v180, v181
	v_mfma_f32_16x16x32_bf16 v[104:107], v[134:137], v[158:161], v[104:107]
	v_mfma_f32_16x16x32_bf16 v[96:99], v[140:143], v[158:161], v[100:103]
	v_mfma_f32_16x16x32_bf16 v[100:103], v[144:147], v[158:161], v[162:165]
	v_mfma_f32_16x16x32_bf16 v[92:95], v[130:133], v[166:169], v[92:95]
	v_mfma_f32_16x16x32_bf16 v[88:91], v[134:137], v[166:169], v[88:91]
	v_mfma_f32_16x16x32_bf16 v[84:87], v[140:143], v[166:169], v[84:87]
	v_mfma_f32_16x16x32_bf16 v[80:83], v[144:147], v[166:169], v[80:83]
	ds_read_b128 v[120:123], v117 offset:4096
	ds_read_b128 v[158:161], v117 offset:5120
	ds_read_b128 v[162:165], v117 offset:6144
	ds_read_b128 v[166:169], v117 offset:7168
	s_waitcnt lgkmcnt(0)
	v_bfe_u32 v117, v138, 5, 1
	v_mfma_f32_16x16x32_bf16 v[60:63], v[130:133], v[120:123], v[60:63]
	s_barrier
	v_mfma_f32_16x16x32_bf16 v[56:59], v[134:137], v[120:123], v[56:59]
	v_mfma_f32_16x16x32_bf16 v[52:55], v[140:143], v[120:123], v[52:55]
	v_mfma_f32_16x16x32_bf16 v[48:51], v[144:147], v[120:123], v[48:51]
	v_lshrrev_b32_e32 v121, 1, v138
	v_lshlrev_b32_e32 v120, 7, v116
	v_and_b32_e32 v121, 8, v121
	v_or3_b32 v122, s15, v120, v121
	v_and_b32_e32 v121, 64, v172
	v_xor_b32_e32 v120, 16, v172
	v_add_u32_e32 v121, 64, v121
	v_cmp_lt_i32_e32 vcc, v120, v121
	v_xor_b32_e32 v123, 32, v172
	v_mfma_f32_16x16x32_bf16 v[76:79], v[130:133], v[174:177], v[76:79]
	v_cndmask_b32_e32 v120, v172, v120, vcc
	v_cmp_lt_i32_e32 vcc, v123, v121
	v_lshlrev_b32_e32 v120, 2, v120
	v_mfma_f32_16x16x32_bf16 v[44:47], v[130:133], v[158:161], v[44:47]
	v_cndmask_b32_e32 v121, v172, v123, vcc
	v_bitop3_b32 v123, v117, v138, 7 bitop3:0x78
	v_lshlrev_b32_e32 v123, 4, v123
	v_or_b32_e32 v126, v122, v123
	s_waitcnt vmcnt(0)
	ds_write_b64 v126, v[124:125]
	v_mul_f32_e32 v124, v179, v179
	v_fmac_f32_e32 v124, v178, v178
	v_fmac_f32_e32 v124, v180, v180
	v_bitop3_b32 v125, v117, v119, 2 bitop3:0x36
	v_fmac_f32_e32 v124, v181, v181
	v_lshlrev_b32_e32 v125, 4, v125
	v_add_f32_e32 v124, v128, v124
	v_cvt_pk_bf16_f32 v126, v178, v179
	v_or_b32_e32 v128, v122, v125
	ds_write_b64 v128, v[126:127]
	v_mul_f32_e32 v126, v183, v183
	v_fmac_f32_e32 v126, v182, v182
	v_fmac_f32_e32 v126, v184, v184
	v_fmac_f32_e32 v126, v185, v185
	v_add_f32_e32 v128, v124, v126
	v_bitop3_b32 v124, v117, v119, 4 bitop3:0x36
	v_lshlrev_b32_e32 v124, 4, v124
	v_mfma_f32_16x16x32_bf16 v[28:31], v[130:133], v[162:165], v[28:31]
	v_cvt_pk_bf16_f32 v126, v182, v183
	v_cvt_pk_bf16_f32 v127, v184, v185
	v_lshlrev_b32_e32 v121, 2, v121
	v_mfma_f32_16x16x32_bf16 v[12:15], v[130:133], v[166:169], v[12:15]
	v_or_b32_e32 v130, v122, v124
	ds_write_b64 v130, v[126:127]
	v_mul_f32_e32 v126, v113, v113
	v_fmac_f32_e32 v126, v112, v112
	v_fmac_f32_e32 v126, v114, v114
	v_fmac_f32_e32 v126, v115, v115
	v_add_f32_e32 v128, v128, v126
	v_cvt_pk_bf16_f32 v126, v112, v113
	v_bitop3_b32 v112, v117, v119, 6 bitop3:0x36
	v_lshlrev_b32_e32 v112, 4, v112
	v_cvt_pk_bf16_f32 v127, v114, v115
	v_or_b32_e32 v113, v122, v112
	ds_write_b64 v113, v[126:127]
	ds_bpermute_b32 v113, v120, v128
	v_mfma_f32_16x16x32_bf16 v[72:75], v[134:137], v[174:177], v[72:75]
	v_cmp_gt_u32_e32 vcc, 16, v118
	v_or_b32_e32 v116, s8, v116
	s_waitcnt lgkmcnt(0)
	v_add_f32_e32 v113, v128, v113
	ds_bpermute_b32 v114, v121, v113
	v_mfma_f32_16x16x32_bf16 v[68:71], v[140:143], v[174:177], v[68:71]
	v_mfma_f32_16x16x32_bf16 v[64:67], v[144:147], v[174:177], v[64:67]
	v_mfma_f32_16x16x32_bf16 v[40:43], v[134:137], v[158:161], v[40:43]
	v_mfma_f32_16x16x32_bf16 v[36:39], v[140:143], v[158:161], v[36:39]
	v_mfma_f32_16x16x32_bf16 v[32:35], v[144:147], v[158:161], v[32:35]
	v_mfma_f32_16x16x32_bf16 v[24:27], v[134:137], v[162:165], v[24:27]
	v_mfma_f32_16x16x32_bf16 v[20:23], v[140:143], v[162:165], v[20:23]
	v_mfma_f32_16x16x32_bf16 v[16:19], v[144:147], v[162:165], v[16:19]
	v_mfma_f32_16x16x32_bf16 v[8:11], v[134:137], v[166:169], v[8:11]
	v_mfma_f32_16x16x32_bf16 v[4:7], v[140:143], v[166:169], v[4:7]
	v_mfma_f32_16x16x32_bf16 v[0:3], v[144:147], v[166:169], v[0:3]
	s_and_saveexec_b64 s[6:7], vcc
	s_cbranch_execz .LBB0_1078
	v_ashrrev_i32_e32 v117, 31, v116
	s_waitcnt lgkmcnt(0)
	v_add_f32_e32 v113, v113, v114
	v_lshlrev_b64 v[114:115], 6, v[116:117]
	v_lshl_add_u64 v[114:115], s[64:65], 0, v[114:115]
	v_lshl_add_u64 v[114:115], s[10:11], 2, v[114:115]
	global_store_dword v[114:115], v113, off
